# MLA loop unrolled by six: LDS ring slots become offset immediates (no per-tile address VALU / slot SALU)
# speedup vs baseline: 1.0044x; 1.0017x over previous
; #define ATT_BAR() asm volatile("s_waitcnt lgkmcnt(0)\n\ts_barrier" ::: "memory")
; template <int DQK> __device__ __forceinline__ void causal_pass_pipe(LAS unsigned char* lds, const bf16* K0, int p0, const bf16* K1, int p1, const bf16* V, int pv, int thi,
;         const bf16x8 (&qf)[2][DQK / 32], const int (&tpos)[2], int wave_tmin, int wave_tmax, f32x4 (&o)[2][4], int tid) {
;     ...
;     Stage<DQK> st;
;     {
;         Stage<DQK> st1;
;         stage_load<DQK>(st, K0, p0, K1, p1, V, pv, 0, true, tid);
;         if (thi >= 1) stage_load<DQK>(st1, K0, p0, K1, p1, V, pv, 1, true, tid);
;         stage_store<DQK>(st, lds, true, tid);
;         if (thi >= 1) stage_store<DQK>(st1, lds + SLOT, true, tid);
;     }
;     ATT_BAR();
;     f32x4 sa[2][4], sb[2][4]; bool ca = true, cb = false;
;     x1_tile<DQK>(lds, qf, m, sa, fr, fq);
;     if (63 <= wave_tmin) x2_tile<true>(0, tpos, m, l, o, sa, fq); else x2_tile<false>(0, tpos, m, l, o, sa, fq);
;     int slot = 0;
.LBB0_873:
	s_or_b64 exec, exec, s[14:15]
	v_lshl_add_u64 v[44:45], s[8:9], 0, v[44:45]
	v_lshl_add_u64 v[44:45], v[44:45], 0, v[146:147]
	global_load_dwordx4 v[44:47], v[44:45], off
	v_lshrrev_b32_e32 v51, 3, v50
	v_and_b32_e32 v49, 7, v50
	v_bitop3_b32 v51, v51, v49, 15 bitop3:0x6c
	v_lshlrev_b32_e32 v155, 4, v51
	v_lshlrev_b32_e32 v153, 8, v48
	v_add_u32_e32 v51, 0, v155
	v_add_u32_e32 v51, v51, v153
	v_and_b32_e32 v78, 3, v50
	v_lshlrev_b32_e32 v157, 8, v76
	v_and_b32_e32 v79, 15, v76
	s_waitcnt vmcnt(0) lgkmcnt(0)
	ds_write_b128 v51, v[24:27]
	s_and_saveexec_b64 s[8:9], s[6:7]
	v_bitop3_b32 v52, v78, v79, 8 bitop3:0x36
	v_lshlrev_b32_e32 v52, 4, v52
	v_add3_u32 v52, 0, v52, v157
	ds_write_b128 v52, v[28:31]
	s_or_b64 exec, exec, s[8:9]
	v_lshlrev_b32_e32 v146, 4, v49
	v_mul_lo_u32 v159, v48, s76
	v_add_u32_e32 v48, 0, v146
	v_add_u32_e32 v48, v48, v159
	ds_write_b128 v48, v[32:35] offset:16384
	ds_write_b128 v51, v[36:39] offset:26624
	s_and_saveexec_b64 s[8:9], s[6:7]
	v_bitop3_b32 v36, v78, v79, 8 bitop3:0x36
	v_lshlrev_b32_e32 v36, 4, v36
	v_add3_u32 v36, 0, v36, v157
	ds_write_b128 v36, v[40:43] offset:26624
	s_or_b64 exec, exec, s[8:9]
	v_lshrrev_b32_e32 v36, 4, v50
	v_and_b32_e32 v80, 15, v50
	v_lshlrev_b32_e32 v195, 8, v80
	v_bitop3_b32 v36, v36, v80, 3 bitop3:0x6c
	ds_write_b128 v48, v[44:47] offset:43008
	v_add_u32_e32 v56, 0, v195
	v_lshlrev_b32_e32 v196, 4, v36
	s_waitcnt lgkmcnt(0)
	s_barrier
	s_xor_b64 s[58:59], s[10:11], -1
	v_lshrrev_b32_e32 v72, 6, v144
	s_lshl_b32 s8, s20, 2
	v_readfirstlane_b32 s14, v72
	s_mov_b32 s9, s8
	s_or_b32 s8, s8, 3
	s_lshr_b32 s15, s14, 1
	s_add_i32 s9, s9, s15
	s_cmp_lt_u32 s14, 4
	s_cselect_b32 s63, 1, 0
	s_mov_b32 s49, -1
	s_mov_b32 s60, 0
	s_mov_b32 s61, 0
	s_mov_b32 s62, 0xd000
	v_add_u32_e32 v155, v153, v155
	v_add_u32_e32 v159, v146, v159
	v_add_u32_e32 v159, 0x4000, v159
	v_and_b32_e32 v72, 15, v144
	v_bfe_u32 v73, v144, 4, 2
	v_lshlrev_b32_e32 v74, 8, v72
	v_xor_b32_e32 v75, v73, v72
	v_lshl_add_u32 v199, v75, 4, v74
	v_or_b32_e32 v75, 4, v73
	v_xor_b32_e32 v75, v75, v72
	v_lshl_add_u32 v201, v75, 4, v74
	v_or_b32_e32 v75, 8, v73
	v_xor_b32_e32 v75, v75, v72
	v_lshl_add_u32 v210, v75, 4, v74
	v_lshrrev_b32_e32 v75, 2, v72
	v_lshl_add_u32 v75, v73, 2, v75
	v_mul_u32_u24_e32 v75, 0xa0, v75
	v_and_b32_e32 v74, 3, v72
	v_lshl_add_u32 v251, v74, 3, v75
	v_add_u32_e32 v203, 0x6800, v251
	v_add_u32_e32 v195, 0x6800, v199
	v_add_u32_e32 v196, 0x6800, v201
	v_add_u32_e32 v202, 0x6800, v210
	v_lshlrev_b32_e32 v75, 2, v73
	v_sub_u32_e32 v151, v158, v75
	v_sub_u32_e32 v153, v156, v75
	v_lshrrev_b32_e32 v72, 2, v144
	v_and_b32_e32 v73, 3, v144
	v_or_b32_e32 v74, 8, v73
	v_and_b32_e32 v75, 15, v72
	v_xor_b32_e32 v74, v74, v75
	v_lshlrev_b32_e32 v75, 8, v72
	v_lshl_add_u32 v157, v74, 4, v75
	s_add_u32 s96, s56, s52
	s_addc_u32 s97, s57, s53
	s_add_u32 s96, s96, 0x3802000
	s_addc_u32 s97, s97, 0
	v_lshlrev_b32_e32 v72, 6, v72
	v_lshl_add_u32 v72, v73, 4, v72
	v_mov_b32_e32 v73, 0
	v_lshl_add_u64 v[166:167], s[96:97], 0, v[72:73]
	v_mov_b32_e32 v72, v146
	v_add_u32_e32 v72, 0x40000, v72
	v_lshl_add_u64 v[160:161], v[160:161], 0, v[72:73]
	v_lshl_add_u64 v[162:163], v[162:163], 0, v[72:73]
	global_load_dwordx4 v[60:63], v[160:161], off
	global_load_dwordx4 v[68:71], v[162:163], off
	s_cmp_eq_u32 s63, 0
	s_cbranch_scc1 .Lmla_nok1_0
	global_load_dwordx4 v[64:67], v[166:167], off
.Lmla_nok1_0:
	v_mov_b32_e32 v96, 0
	v_mov_b32_e32 v97, 0
	v_mov_b32_e32 v98, 0
	v_mov_b32_e32 v99, 0
	v_mov_b32_e32 v88, 0
	v_mov_b32_e32 v89, 0
	v_mov_b32_e32 v90, 0
	v_mov_b32_e32 v91, 0
	v_mov_b32_e32 v92, 0
	v_mov_b32_e32 v93, 0
	v_mov_b32_e32 v94, 0
	v_mov_b32_e32 v95, 0
	v_mov_b32_e32 v48, 0
	v_mov_b32_e32 v49, 0
	v_mov_b32_e32 v50, 0
	v_mov_b32_e32 v51, 0
	v_mov_b32_e32 v165, 0
	v_mov_b32_e32 v200, v183
	v_mov_b32_e32 v84, 0
	v_mov_b32_e32 v85, 0
	v_mov_b32_e32 v86, 0
	v_mov_b32_e32 v87, 0
	v_mov_b32_e32 v76, 0
	v_mov_b32_e32 v77, 0
	v_mov_b32_e32 v78, 0
	v_mov_b32_e32 v79, 0
	v_mov_b32_e32 v80, 0
	v_mov_b32_e32 v81, 0
	v_mov_b32_e32 v82, 0
	v_mov_b32_e32 v83, 0
	v_mov_b32_e32 v56, 0
	v_mov_b32_e32 v57, 0
	v_mov_b32_e32 v58, 0
	v_mov_b32_e32 v59, 0
	v_mov_b32_e32 v164, 0
	v_mov_b32_e32 v211, v183
	s_mov_b32 s100, 0x20000
	s_mov_b32 s101, 0
	v_cmp_lt_f32_e64 s[66:67], s77, v200
	v_cmp_lt_f32_e64 s[68:69], s77, v211
	s_nop 1
	v_cndmask_b32_e64 v197, 0, v200, s[66:67]
	v_cndmask_b32_e64 v198, 0, v211, s[68:69]
	s_and_b64 s[64:65], s[66:67], s[68:69]
	v_sub_f32_e32 v204, 0, v197
	v_mov_b32_e32 v205, v204
	v_mov_b32_e32 v206, v204
	v_mov_b32_e32 v207, v204
	v_sub_f32_e32 v252, 0, v198
	v_mov_b32_e32 v253, v252
	v_mov_b32_e32 v254, v252
	v_mov_b32_e32 v255, v252
	ds_read_b128 v[236:239], v199
	ds_read_b128 v[240:243], v201
	ds_read_b128 v[244:247], v210
	s_waitcnt lgkmcnt(0)
	v_mfma_f32_16x16x32_bf16 v[100:103], v[236:239], v[0:3], v[204:207]
	v_mfma_f32_16x16x32_bf16 v[116:119], v[236:239], v[12:15], v[252:255]
	v_mfma_f32_16x16x32_bf16 v[100:103], v[240:243], v[4:7], v[100:103]
	v_mfma_f32_16x16x32_bf16 v[116:119], v[240:243], v[16:19], v[116:119]
	v_mfma_f32_16x16x32_bf16 v[100:103], v[244:247], v[8:11], v[100:103]
	v_mfma_f32_16x16x32_bf16 v[116:119], v[244:247], v[20:23], v[116:119]
	ds_read_b128 v[236:239], v199 offset:4096
	ds_read_b128 v[240:243], v201 offset:4096
	ds_read_b128 v[244:247], v210 offset:4096
	s_waitcnt lgkmcnt(0)
	v_mfma_f32_16x16x32_bf16 v[104:107], v[236:239], v[0:3], v[204:207]
	v_mfma_f32_16x16x32_bf16 v[120:123], v[236:239], v[12:15], v[252:255]
	v_mfma_f32_16x16x32_bf16 v[104:107], v[240:243], v[4:7], v[104:107]
	v_mfma_f32_16x16x32_bf16 v[120:123], v[240:243], v[16:19], v[120:123]
	v_mfma_f32_16x16x32_bf16 v[104:107], v[244:247], v[8:11], v[104:107]
	v_mfma_f32_16x16x32_bf16 v[120:123], v[244:247], v[20:23], v[120:123]
	ds_read_b128 v[236:239], v199 offset:8192
	ds_read_b128 v[240:243], v201 offset:8192
	ds_read_b128 v[244:247], v210 offset:8192
	s_waitcnt lgkmcnt(0)
	v_mfma_f32_16x16x32_bf16 v[108:111], v[236:239], v[0:3], v[204:207]
	v_mfma_f32_16x16x32_bf16 v[124:127], v[236:239], v[12:15], v[252:255]
	v_mfma_f32_16x16x32_bf16 v[108:111], v[240:243], v[4:7], v[108:111]
	v_mfma_f32_16x16x32_bf16 v[124:127], v[240:243], v[16:19], v[124:127]
	v_mfma_f32_16x16x32_bf16 v[108:111], v[244:247], v[8:11], v[108:111]
	v_mfma_f32_16x16x32_bf16 v[124:127], v[244:247], v[20:23], v[124:127]
	ds_read_b128 v[236:239], v199 offset:12288
	ds_read_b128 v[240:243], v201 offset:12288
	ds_read_b128 v[244:247], v210 offset:12288
	s_waitcnt lgkmcnt(0)
	v_mfma_f32_16x16x32_bf16 v[112:115], v[236:239], v[0:3], v[204:207]
	v_mfma_f32_16x16x32_bf16 v[128:131], v[236:239], v[12:15], v[252:255]
	v_mfma_f32_16x16x32_bf16 v[112:115], v[240:243], v[4:7], v[112:115]
	v_mfma_f32_16x16x32_bf16 v[128:131], v[240:243], v[16:19], v[128:131]
	v_mfma_f32_16x16x32_bf16 v[112:115], v[244:247], v[8:11], v[112:115]
	v_mfma_f32_16x16x32_bf16 v[128:131], v[244:247], v[20:23], v[128:131]
	s_nop 7
	s_nop 7
	s_add_i32 s32, s49, 1
	s_cmp_eq_u32 s32, s9
	s_cbranch_scc1 .Lmla_mask5
	s_branch .Lmla_slow5_0
; #define LAS __attribute__((address_space(3)))
; template <int DQK> __device__ __forceinline__ void stage_load(Stage<DQK>& s, const bf16* K0, int p0, const bf16* K1, int p1, const bf16* V, int pv, int tile, bool withV, int tid) {
;     { const int key = tid >> 3, c = tid & 7; s.k0 = *(const v4u*)(K0 + (size_t)(64 * tile + key) * p0 + 8 * c); }
;     if (DQK == 96) { if (tid < 256) { const int key = tid >> 2, c = tid & 3; s.k1 = *(const v4u*)(K1 + (size_t)(64 * tile + key) * p1 + 8 * c); } }
;     if (withV) { const int key = tid >> 3, c = tid & 7; s.v = *(const v4u*)(V + (size_t)(64 * tile + key) * pv + 8 * c); }
; }
; template <int DQK, int VO = KL<DQK>::VOFF> __device__ __forceinline__ void stage_store(const Stage<DQK>& s, LAS unsigned char* lds, bool withV, int tid) {
;     { const int key = tid >> 3, c = tid & 7; *(LAS v4u*)(lds + k_off<DQK>(key, c)) = s.k0; }
;     if (DQK == 96) { if (tid < 256) { const int key = tid >> 2, c = tid & 3; *(LAS v4u*)(lds + k_off<DQK>(key, 8 + c)) = s.k1; } }
;     if (withV) { const int key = tid >> 3, c = tid & 7; *(LAS v4u*)(lds + VO + (key * VSTR + 8 * c) * 2) = s.v; }
.Lmla_it0:
	s_add_i32 s96, s49, 2
	s_cmp_gt_u32 s96, s8
	s_cbranch_scc1 .Lmla_nostage0
	s_waitcnt vmcnt(0)
	ds_write_b128 v155, v[60:63] offset:53248
	ds_write_b128 v159, v[68:71] offset:53248
	s_cmp_eq_u32 s63, 0
	s_cbranch_scc1 .Lmla_nok1_10
	ds_write_b128 v157, v[64:67] offset:53248
.Lmla_nok1_10:
	s_cmp_ge_u32 s96, s8
	s_cbranch_scc1 .Lmla_nostage0
	v_lshl_add_u64 v[160:161], v[160:161], 0, s[100:101]
	v_lshl_add_u64 v[162:163], v[162:163], 0, s[100:101]
	global_load_dwordx4 v[60:63], v[160:161], off
	global_load_dwordx4 v[68:71], v[162:163], off
	s_cmp_eq_u32 s63, 0
	s_cbranch_scc1 .Lmla_nostage0
	v_add_co_u32_e32 v166, vcc, 0x1000, v166
	s_nop 0
	v_addc_co_u32_e32 v167, vcc, 0, v167, vcc
	global_load_dwordx4 v[64:67], v[166:167], off
; #define LAS __attribute__((address_space(3)))
; template <int I0, int NQ, int VO> __device__ __forceinline__ void tile_y(LAS unsigned char* lds, float (&l)[2], f32x4 (&o)[2][4], f32x4 (&s)[2][4], int fr, int fq) {
;     bf16x8 pb[NQ][2];
; #pragma unroll
;     for (int q = 0; q < NQ; ++q) {
;         f32x4 (&sq)[4] = s[I0 + q];
;         f32x2_t rs2 = {0.f, 0.f};
; #pragma unroll
;         for (int ss = 0; ss < 4; ++ss) {
; #pragma unroll
;             for (int i = 0; i < 4; ++i) sq[ss][i] = __builtin_amdgcn_exp2f(sq[ss][i]);
;             rs2 += (f32x2_t){sq[ss][0], sq[ss][1]}; rs2 += (f32x2_t){sq[ss][2], sq[ss][3]};
;         }
;         l[I0 + q] += rs2.x + rs2.y;
; #pragma unroll
;         for (int j = 0; j < 2; ++j) {
;             const v4u w = (v4u){cvtpk(sq[2 * j][0], sq[2 * j][1]), cvtpk(sq[2 * j][2], sq[2 * j][3]), cvtpk(sq[2 * j + 1][0], sq[2 * j + 1][1]), cvtpk(sq[2 * j + 1][2], sq[2 * j + 1][3])};
;             pb[q][j] = __builtin_bit_cast(bf16x8, w);
;         }
;     }
; #pragma unroll
;     for (int dt = 0; dt < 4; ++dt)
; #pragma unroll
;         for (int j = 0; j < 2; ++j) {
;             LAS unsigned char* vp = lds + VO + ((32 * j + 4 * fq + (fr >> 2)) * VSTR + 16 * dt + 4 * (fr & 3)) * 2;
;             const s16x4 lo = __builtin_bit_cast(s16x4, __builtin_amdgcn_ds_read_tr16_b64_v4i16((LAS v4i16_t*)vp));
;             const s16x4 hi = __builtin_bit_cast(s16x4, __builtin_amdgcn_ds_read_tr16_b64_v4i16((LAS v4i16_t*)(vp + 16 * VSTR * 2)));
;             const bf16x8 vf = (bf16x8){lo[0], lo[1], lo[2], lo[3], hi[0], hi[1], hi[2], hi[3]};
; #pragma unroll
; template <int DQK> __device__ __forceinline__ void x1_tile(LAS unsigned char* lds, const bf16x8 (&qf)[2][DQK / 32], const float (&m)[2], f32x4 (&s)[2][4], int fr, int fq) {
;     constexpr int NKS = DQK / 32;
; #pragma unroll
;     for (int q = 0; q < 2; ++q) { const float c = (m[q] > -1e29f) ? -m[q] : 0.f;
; #pragma unroll
;         for (int ss = 0; ss < 4; ++ss) s[q][ss] = (f32x4){c, c, c, c}; }
; #pragma unroll
;     for (int ss = 0; ss < 4; ++ss)
; #pragma unroll
;         for (int ks = 0; ks < NKS; ++ks) {
;             const bf16x8 kf = *(const LAS bf16x8*)(lds + k_off<DQK>(16 * ss + fr, 4 * ks + fq));
; #pragma unroll
;             for (int q = 0; q < 2; ++q) s[q][ss] = __builtin_amdgcn_mfma_f32_16x16x32_bf16(kf, qf[q][ks], s[q][ss], 0, 0, 0);
;         }
; }
.Lmla_nostage0:
	s_cmp_ge_u32 s49, s9
	s_cbranch_scc1 .Lmla_tail0
	ds_read_b64_tr_b16 v[220:221], v251 offset:16384
	ds_read_b64_tr_b16 v[222:223], v251 offset:18944
	ds_read_b64_tr_b16 v[224:225], v251 offset:21504
	ds_read_b64_tr_b16 v[226:227], v251 offset:24064
	ds_read_b64_tr_b16 v[228:229], v251 offset:16416
	ds_read_b64_tr_b16 v[230:231], v251 offset:18976
	ds_read_b64_tr_b16 v[232:233], v251 offset:21536
	ds_read_b64_tr_b16 v[234:235], v251 offset:24096
	ds_read_b128 v[236:239], v195
	ds_read_b128 v[240:243], v196
	ds_read_b128 v[244:247], v202
	s_waitcnt lgkmcnt(2)
	v_mfma_f32_16x16x32_bf16 v[24:27], v[236:239], v[0:3], v[204:207]
	v_exp_f32_e32 v100, v100
	v_mfma_f32_16x16x32_bf16 v[40:43], v[236:239], v[12:15], v[252:255]
	v_exp_f32_e32 v101, v101
	ds_read_b128 v[236:239], v195 offset:4096
	s_waitcnt lgkmcnt(2)
	v_mfma_f32_16x16x32_bf16 v[24:27], v[240:243], v[4:7], v[24:27]
	v_exp_f32_e32 v102, v102
	v_mfma_f32_16x16x32_bf16 v[40:43], v[240:243], v[16:19], v[40:43]
	v_exp_f32_e32 v103, v103
	ds_read_b128 v[240:243], v196 offset:4096
	s_waitcnt lgkmcnt(2)
	v_mfma_f32_16x16x32_bf16 v[24:27], v[244:247], v[8:11], v[24:27]
	v_exp_f32_e32 v104, v104
	v_mfma_f32_16x16x32_bf16 v[40:43], v[244:247], v[20:23], v[40:43]
	v_exp_f32_e32 v105, v105
	ds_read_b128 v[244:247], v202 offset:4096
	s_waitcnt lgkmcnt(2)
	v_mfma_f32_16x16x32_bf16 v[28:31], v[236:239], v[0:3], v[204:207]
	v_exp_f32_e32 v106, v106
	v_mfma_f32_16x16x32_bf16 v[44:47], v[236:239], v[12:15], v[252:255]
	v_exp_f32_e32 v107, v107
	ds_read_b128 v[236:239], v195 offset:8192
	s_waitcnt lgkmcnt(2)
	v_mfma_f32_16x16x32_bf16 v[28:31], v[240:243], v[4:7], v[28:31]
	v_exp_f32_e32 v108, v108
	v_mfma_f32_16x16x32_bf16 v[44:47], v[240:243], v[16:19], v[44:47]
	v_exp_f32_e32 v109, v109
	ds_read_b128 v[240:243], v196 offset:8192
	s_waitcnt lgkmcnt(2)
	v_mfma_f32_16x16x32_bf16 v[28:31], v[244:247], v[8:11], v[28:31]
	v_exp_f32_e32 v110, v110
	v_mfma_f32_16x16x32_bf16 v[44:47], v[244:247], v[20:23], v[44:47]
	v_exp_f32_e32 v111, v111
	ds_read_b128 v[244:247], v202 offset:8192
	s_waitcnt lgkmcnt(2)
	v_mfma_f32_16x16x32_bf16 v[32:35], v[236:239], v[0:3], v[204:207]
	v_exp_f32_e32 v112, v112
	v_mfma_f32_16x16x32_bf16 v[212:215], v[236:239], v[12:15], v[252:255]
	v_exp_f32_e32 v113, v113
	ds_read_b128 v[236:239], v195 offset:12288
	s_waitcnt lgkmcnt(2)
	v_mfma_f32_16x16x32_bf16 v[32:35], v[240:243], v[4:7], v[32:35]
	v_exp_f32_e32 v114, v114
	v_mfma_f32_16x16x32_bf16 v[212:215], v[240:243], v[16:19], v[212:215]
	v_exp_f32_e32 v115, v115
	ds_read_b128 v[240:243], v196 offset:12288
	s_waitcnt lgkmcnt(2)
	v_mfma_f32_16x16x32_bf16 v[32:35], v[244:247], v[8:11], v[32:35]
	v_cvt_pk_bf16_f32 v132, v100, v101
	v_cvt_pk_bf16_f32 v133, v102, v103
	v_mfma_f32_16x16x32_bf16 v[212:215], v[244:247], v[20:23], v[212:215]
	v_cvt_pk_bf16_f32 v134, v104, v105
	v_cvt_pk_bf16_f32 v135, v106, v107
	ds_read_b128 v[244:247], v202 offset:12288
	s_waitcnt lgkmcnt(2)
	v_mfma_f32_16x16x32_bf16 v[36:39], v[236:239], v[0:3], v[204:207]
	v_cvt_pk_bf16_f32 v136, v108, v109
	v_cvt_pk_bf16_f32 v137, v110, v111
	v_mfma_f32_16x16x32_bf16 v[216:219], v[236:239], v[12:15], v[252:255]
	v_cvt_pk_bf16_f32 v138, v112, v113
	v_cvt_pk_bf16_f32 v139, v114, v115
	ds_read_b64_tr_b16 v[236:237], v251 offset:16448
	ds_read_b64_tr_b16 v[238:239], v251 offset:19008
	s_waitcnt lgkmcnt(3)
	v_mfma_f32_16x16x32_bf16 v[36:39], v[240:243], v[4:7], v[36:39]
	v_exp_f32_e32 v116, v116
	v_mfma_f32_16x16x32_bf16 v[216:219], v[240:243], v[16:19], v[216:219]
	v_exp_f32_e32 v117, v117
	ds_read_b64_tr_b16 v[240:241], v251 offset:21568
	ds_read_b64_tr_b16 v[242:243], v251 offset:24128
	s_waitcnt lgkmcnt(4)
	v_mfma_f32_16x16x32_bf16 v[36:39], v[244:247], v[8:11], v[36:39]
	v_exp_f32_e32 v118, v118
	v_mfma_f32_16x16x32_bf16 v[216:219], v[244:247], v[20:23], v[216:219]
	v_exp_f32_e32 v119, v119
	ds_read_b64_tr_b16 v[244:245], v251 offset:16480
	ds_read_b64_tr_b16 v[246:247], v251 offset:19040
	v_exp_f32_e32 v120, v120
	v_exp_f32_e32 v121, v121
	v_exp_f32_e32 v122, v122
	v_exp_f32_e32 v123, v123
	v_exp_f32_e32 v124, v124
	v_exp_f32_e32 v125, v125
	v_exp_f32_e32 v126, v126
	v_exp_f32_e32 v127, v127
	v_exp_f32_e32 v128, v128
	v_exp_f32_e32 v129, v129
	v_exp_f32_e32 v130, v130
	v_exp_f32_e32 v131, v131
	v_cvt_pk_bf16_f32 v140, v116, v117
	v_cvt_pk_bf16_f32 v141, v118, v119
	v_cvt_pk_bf16_f32 v142, v120, v121
	v_cvt_pk_bf16_f32 v143, v122, v123
	v_cvt_pk_bf16_f32 v52, v124, v125
	v_cvt_pk_bf16_f32 v53, v126, v127
	v_cvt_pk_bf16_f32 v54, v128, v129
	v_cvt_pk_bf16_f32 v55, v130, v131
	s_waitcnt lgkmcnt(15)
	v_mfma_f32_16x16x32_bf16 v[96:99], v[220:223], v[132:135], v[96:99]
	v_add_f32_e32 v100, v100, v101
	v_add_f32_e32 v102, v102, v103
	v_mfma_f32_16x16x32_bf16 v[84:87], v[220:223], v[140:143], v[84:87]
	v_add_f32_e32 v104, v104, v105
	v_add_f32_e32 v106, v106, v107
	s_waitcnt lgkmcnt(15)
	v_mfma_f32_16x16x32_bf16 v[96:99], v[224:227], v[136:139], v[96:99]
	v_add_f32_e32 v108, v108, v109
	v_add_f32_e32 v110, v110, v111
	v_mfma_f32_16x16x32_bf16 v[84:87], v[224:227], v[52:55], v[84:87]
	v_add_f32_e32 v112, v112, v113
	v_add_f32_e32 v114, v114, v115
	ds_read_b64_tr_b16 v[220:221], v251 offset:21600
	ds_read_b64_tr_b16 v[222:223], v251 offset:24160
	s_waitcnt lgkmcnt(15)
	v_mfma_f32_16x16x32_bf16 v[88:91], v[228:231], v[132:135], v[88:91]
	v_add_f32_e32 v100, v100, v102
	v_add_f32_e32 v104, v104, v106
	v_mfma_f32_16x16x32_bf16 v[76:79], v[228:231], v[140:143], v[76:79]
	v_add_f32_e32 v108, v108, v110
	v_add_f32_e32 v112, v112, v114
	s_waitcnt lgkmcnt(15)
	v_mfma_f32_16x16x32_bf16 v[88:91], v[232:235], v[136:139], v[88:91]
	v_add_f32_e32 v100, v100, v104
	v_add_f32_e32 v108, v108, v112
	v_mfma_f32_16x16x32_bf16 v[76:79], v[232:235], v[52:55], v[76:79]
	v_add_f32_e32 v100, v100, v108
	v_add_f32_e32 v165, v165, v100
	s_waitcnt lgkmcnt(6)
	v_mfma_f32_16x16x32_bf16 v[92:95], v[236:239], v[132:135], v[92:95]
	v_add_f32_e32 v116, v116, v117
	v_add_f32_e32 v118, v118, v119
	v_mfma_f32_16x16x32_bf16 v[80:83], v[236:239], v[140:143], v[80:83]
	v_add_f32_e32 v120, v120, v121
	v_add_f32_e32 v122, v122, v123
	s_waitcnt lgkmcnt(4)
	v_mfma_f32_16x16x32_bf16 v[92:95], v[240:243], v[136:139], v[92:95]
	v_add_f32_e32 v124, v124, v125
	v_add_f32_e32 v126, v126, v127
	v_mfma_f32_16x16x32_bf16 v[80:83], v[240:243], v[52:55], v[80:83]
	v_add_f32_e32 v128, v128, v129
	v_add_f32_e32 v130, v130, v131
	s_waitcnt lgkmcnt(2)
	v_mfma_f32_16x16x32_bf16 v[48:51], v[244:247], v[132:135], v[48:51]
	v_add_f32_e32 v116, v116, v118
	v_add_f32_e32 v120, v120, v122
	v_mfma_f32_16x16x32_bf16 v[56:59], v[244:247], v[140:143], v[56:59]
	v_add_f32_e32 v124, v124, v126
	v_add_f32_e32 v128, v128, v130
	s_waitcnt lgkmcnt(0)
	v_mfma_f32_16x16x32_bf16 v[48:51], v[220:223], v[136:139], v[48:51]
	v_add_f32_e32 v116, v116, v120
	v_add_f32_e32 v124, v124, v128
	v_mfma_f32_16x16x32_bf16 v[56:59], v[220:223], v[52:55], v[56:59]
	v_add_f32_e32 v116, v116, v124
	v_add_f32_e32 v164, v164, v116
	s_add_i32 s32, s49, 1
	s_cmp_eq_u32 s32, s9
	s_cbranch_scc1 .Lmla_mask0

; #define LAS __attribute__((address_space(3)))
; template <int DQK, int VO = KL<DQK>::VOFF> __device__ __forceinline__ void stage_store(const Stage<DQK>& s, LAS unsigned char* lds, bool withV, int tid) {
;     { const int key = tid >> 3, c = tid & 7; *(LAS v4u*)(lds + k_off<DQK>(key, c)) = s.k0; }
;     if (DQK == 96) { if (tid < 256) { const int key = tid >> 2, c = tid & 3; *(LAS v4u*)(lds + k_off<DQK>(key, 8 + c)) = s.k1; } }
;     if (withV) { const int key = tid >> 3, c = tid & 7; *(LAS v4u*)(lds + VO + (key * VSTR + 8 * c) * 2) = s.v; }
.Lmla_bar0:
	s_waitcnt lgkmcnt(0)
	s_barrier
	s_add_i32 s49, s49, 1
	s_cmp_le_u32 s49, s8
	s_cbranch_scc1 .Lmla_it1
	s_branch .Lmla_exit
.Lmla_it1:
	s_add_i32 s96, s49, 2
	s_cmp_gt_u32 s96, s8
	s_cbranch_scc1 .Lmla_nostage1
	s_waitcnt vmcnt(0)
	ds_write_b128 v155, v[60:63]
	ds_write_b128 v159, v[68:71]
	s_cmp_eq_u32 s63, 0
	s_cbranch_scc1 .Lmla_nok1_11
	ds_write_b128 v157, v[64:67]

; #define LAS __attribute__((address_space(3)))
; template <int I0, int NQ, int VO> __device__ __forceinline__ void tile_y(LAS unsigned char* lds, float (&l)[2], f32x4 (&o)[2][4], f32x4 (&s)[2][4], int fr, int fq) {
;     bf16x8 pb[NQ][2];
; #pragma unroll
;     for (int q = 0; q < NQ; ++q) {
;         f32x4 (&sq)[4] = s[I0 + q];
;         f32x2_t rs2 = {0.f, 0.f};
; #pragma unroll
;         for (int ss = 0; ss < 4; ++ss) {
; #pragma unroll
;             for (int i = 0; i < 4; ++i) sq[ss][i] = __builtin_amdgcn_exp2f(sq[ss][i]);
;             rs2 += (f32x2_t){sq[ss][0], sq[ss][1]}; rs2 += (f32x2_t){sq[ss][2], sq[ss][3]};
;         }
;         l[I0 + q] += rs2.x + rs2.y;
; #pragma unroll
;         for (int j = 0; j < 2; ++j) {
;             const v4u w = (v4u){cvtpk(sq[2 * j][0], sq[2 * j][1]), cvtpk(sq[2 * j][2], sq[2 * j][3]), cvtpk(sq[2 * j + 1][0], sq[2 * j + 1][1]), cvtpk(sq[2 * j + 1][2], sq[2 * j + 1][3])};
;             pb[q][j] = __builtin_bit_cast(bf16x8, w);
;         }
;     }
; #pragma unroll
;     for (int dt = 0; dt < 4; ++dt)
; #pragma unroll
;         for (int j = 0; j < 2; ++j) {
;             LAS unsigned char* vp = lds + VO + ((32 * j + 4 * fq + (fr >> 2)) * VSTR + 16 * dt + 4 * (fr & 3)) * 2;
;             const s16x4 lo = __builtin_bit_cast(s16x4, __builtin_amdgcn_ds_read_tr16_b64_v4i16((LAS v4i16_t*)vp));
;             const s16x4 hi = __builtin_bit_cast(s16x4, __builtin_amdgcn_ds_read_tr16_b64_v4i16((LAS v4i16_t*)(vp + 16 * VSTR * 2)));
;             const bf16x8 vf = (bf16x8){lo[0], lo[1], lo[2], lo[3], hi[0], hi[1], hi[2], hi[3]};
; #pragma unroll
; template <int DQK> __device__ __forceinline__ void x1_tile(LAS unsigned char* lds, const bf16x8 (&qf)[2][DQK / 32], const float (&m)[2], f32x4 (&s)[2][4], int fr, int fq) {
;     constexpr int NKS = DQK / 32;
; #pragma unroll
;     for (int q = 0; q < 2; ++q) { const float c = (m[q] > -1e29f) ? -m[q] : 0.f;
; #pragma unroll
;         for (int ss = 0; ss < 4; ++ss) s[q][ss] = (f32x4){c, c, c, c}; }
; #pragma unroll
;     for (int ss = 0; ss < 4; ++ss)
; #pragma unroll
;         for (int ks = 0; ks < NKS; ++ks) {
;             const bf16x8 kf = *(const LAS bf16x8*)(lds + k_off<DQK>(16 * ss + fr, 4 * ks + fq));
; #pragma unroll
;             for (int q = 0; q < 2; ++q) s[q][ss] = __builtin_amdgcn_mfma_f32_16x16x32_bf16(kf, qf[q][ks], s[q][ss], 0, 0, 0);
;         }
; }
.Lmla_nostage1:
	s_cmp_ge_u32 s49, s9
	s_cbranch_scc1 .Lmla_tail1
	ds_read_b64_tr_b16 v[220:221], v203 offset:16384
	ds_read_b64_tr_b16 v[222:223], v203 offset:18944
	ds_read_b64_tr_b16 v[224:225], v203 offset:21504
	ds_read_b64_tr_b16 v[226:227], v203 offset:24064
	ds_read_b64_tr_b16 v[228:229], v203 offset:16416
	ds_read_b64_tr_b16 v[230:231], v203 offset:18976
	ds_read_b64_tr_b16 v[232:233], v203 offset:21536
	ds_read_b64_tr_b16 v[234:235], v203 offset:24096
	ds_read_b128 v[236:239], v195 offset:26624
	ds_read_b128 v[240:243], v196 offset:26624
	ds_read_b128 v[244:247], v202 offset:26624
	s_waitcnt lgkmcnt(2)
	v_mfma_f32_16x16x32_bf16 v[100:103], v[236:239], v[0:3], v[204:207]
	v_exp_f32_e32 v24, v24
	v_mfma_f32_16x16x32_bf16 v[116:119], v[236:239], v[12:15], v[252:255]
	v_exp_f32_e32 v25, v25
	ds_read_b128 v[236:239], v195 offset:30720
	s_waitcnt lgkmcnt(2)
	v_mfma_f32_16x16x32_bf16 v[100:103], v[240:243], v[4:7], v[100:103]
	v_exp_f32_e32 v26, v26
	v_mfma_f32_16x16x32_bf16 v[116:119], v[240:243], v[16:19], v[116:119]
	v_exp_f32_e32 v27, v27
	ds_read_b128 v[240:243], v196 offset:30720
	s_waitcnt lgkmcnt(2)
	v_mfma_f32_16x16x32_bf16 v[100:103], v[244:247], v[8:11], v[100:103]
	v_exp_f32_e32 v28, v28
	v_mfma_f32_16x16x32_bf16 v[116:119], v[244:247], v[20:23], v[116:119]
	v_exp_f32_e32 v29, v29
	ds_read_b128 v[244:247], v202 offset:30720
	s_waitcnt lgkmcnt(2)
	v_mfma_f32_16x16x32_bf16 v[104:107], v[236:239], v[0:3], v[204:207]
	v_exp_f32_e32 v30, v30
	v_mfma_f32_16x16x32_bf16 v[120:123], v[236:239], v[12:15], v[252:255]
	v_exp_f32_e32 v31, v31
	ds_read_b128 v[236:239], v195 offset:34816
	s_waitcnt lgkmcnt(2)
	v_mfma_f32_16x16x32_bf16 v[104:107], v[240:243], v[4:7], v[104:107]
	v_exp_f32_e32 v32, v32
	v_mfma_f32_16x16x32_bf16 v[120:123], v[240:243], v[16:19], v[120:123]
	v_exp_f32_e32 v33, v33
	ds_read_b128 v[240:243], v196 offset:34816
	s_waitcnt lgkmcnt(2)
	v_mfma_f32_16x16x32_bf16 v[104:107], v[244:247], v[8:11], v[104:107]
	v_exp_f32_e32 v34, v34
	v_mfma_f32_16x16x32_bf16 v[120:123], v[244:247], v[20:23], v[120:123]
	v_exp_f32_e32 v35, v35
	ds_read_b128 v[244:247], v202 offset:34816
	s_waitcnt lgkmcnt(2)
	v_mfma_f32_16x16x32_bf16 v[108:111], v[236:239], v[0:3], v[204:207]
	v_exp_f32_e32 v36, v36
	v_mfma_f32_16x16x32_bf16 v[124:127], v[236:239], v[12:15], v[252:255]
	v_exp_f32_e32 v37, v37
	ds_read_b128 v[236:239], v195 offset:38912
	s_waitcnt lgkmcnt(2)
	v_mfma_f32_16x16x32_bf16 v[108:111], v[240:243], v[4:7], v[108:111]
	v_exp_f32_e32 v38, v38
	v_mfma_f32_16x16x32_bf16 v[124:127], v[240:243], v[16:19], v[124:127]
	v_exp_f32_e32 v39, v39
	ds_read_b128 v[240:243], v196 offset:38912
	s_waitcnt lgkmcnt(2)
	v_mfma_f32_16x16x32_bf16 v[108:111], v[244:247], v[8:11], v[108:111]
	v_cvt_pk_bf16_f32 v132, v24, v25
	v_cvt_pk_bf16_f32 v133, v26, v27
	v_mfma_f32_16x16x32_bf16 v[124:127], v[244:247], v[20:23], v[124:127]
	v_cvt_pk_bf16_f32 v134, v28, v29
	v_cvt_pk_bf16_f32 v135, v30, v31
	ds_read_b128 v[244:247], v202 offset:38912
	s_waitcnt lgkmcnt(2)
	v_mfma_f32_16x16x32_bf16 v[112:115], v[236:239], v[0:3], v[204:207]
	v_cvt_pk_bf16_f32 v136, v32, v33
	v_cvt_pk_bf16_f32 v137, v34, v35
	v_mfma_f32_16x16x32_bf16 v[128:131], v[236:239], v[12:15], v[252:255]
	v_cvt_pk_bf16_f32 v138, v36, v37
	v_cvt_pk_bf16_f32 v139, v38, v39
	ds_read_b64_tr_b16 v[236:237], v203 offset:16448
	ds_read_b64_tr_b16 v[238:239], v203 offset:19008
	s_waitcnt lgkmcnt(3)
	v_mfma_f32_16x16x32_bf16 v[112:115], v[240:243], v[4:7], v[112:115]
	v_exp_f32_e32 v40, v40
	v_mfma_f32_16x16x32_bf16 v[128:131], v[240:243], v[16:19], v[128:131]
	v_exp_f32_e32 v41, v41
	ds_read_b64_tr_b16 v[240:241], v203 offset:21568
	ds_read_b64_tr_b16 v[242:243], v203 offset:24128
	s_waitcnt lgkmcnt(4)
	v_mfma_f32_16x16x32_bf16 v[112:115], v[244:247], v[8:11], v[112:115]
	v_exp_f32_e32 v42, v42
	v_mfma_f32_16x16x32_bf16 v[128:131], v[244:247], v[20:23], v[128:131]
	v_exp_f32_e32 v43, v43
	ds_read_b64_tr_b16 v[244:245], v203 offset:16480
	ds_read_b64_tr_b16 v[246:247], v203 offset:19040
	v_exp_f32_e32 v44, v44
	v_exp_f32_e32 v45, v45
	v_exp_f32_e32 v46, v46
	v_exp_f32_e32 v47, v47
	v_exp_f32_e32 v212, v212
	v_exp_f32_e32 v213, v213
	v_exp_f32_e32 v214, v214
	v_exp_f32_e32 v215, v215
	v_exp_f32_e32 v216, v216
	v_exp_f32_e32 v217, v217
	v_exp_f32_e32 v218, v218
	v_exp_f32_e32 v219, v219
	v_cvt_pk_bf16_f32 v140, v40, v41
	v_cvt_pk_bf16_f32 v141, v42, v43
	v_cvt_pk_bf16_f32 v142, v44, v45
	v_cvt_pk_bf16_f32 v143, v46, v47
	v_cvt_pk_bf16_f32 v52, v212, v213
	v_cvt_pk_bf16_f32 v53, v214, v215
	v_cvt_pk_bf16_f32 v54, v216, v217
	v_cvt_pk_bf16_f32 v55, v218, v219
	s_waitcnt lgkmcnt(15)
	v_mfma_f32_16x16x32_bf16 v[96:99], v[220:223], v[132:135], v[96:99]
	v_add_f32_e32 v24, v24, v25
	v_add_f32_e32 v26, v26, v27
	v_mfma_f32_16x16x32_bf16 v[84:87], v[220:223], v[140:143], v[84:87]
	v_add_f32_e32 v28, v28, v29
	v_add_f32_e32 v30, v30, v31
	s_waitcnt lgkmcnt(15)
	v_mfma_f32_16x16x32_bf16 v[96:99], v[224:227], v[136:139], v[96:99]
	v_add_f32_e32 v32, v32, v33
	v_add_f32_e32 v34, v34, v35
	v_mfma_f32_16x16x32_bf16 v[84:87], v[224:227], v[52:55], v[84:87]
	v_add_f32_e32 v36, v36, v37
	v_add_f32_e32 v38, v38, v39
	ds_read_b64_tr_b16 v[220:221], v203 offset:21600
	ds_read_b64_tr_b16 v[222:223], v203 offset:24160
	s_waitcnt lgkmcnt(15)
	v_mfma_f32_16x16x32_bf16 v[88:91], v[228:231], v[132:135], v[88:91]
	v_add_f32_e32 v24, v24, v26
	v_add_f32_e32 v28, v28, v30
	v_mfma_f32_16x16x32_bf16 v[76:79], v[228:231], v[140:143], v[76:79]
	v_add_f32_e32 v32, v32, v34
	v_add_f32_e32 v36, v36, v38
	s_waitcnt lgkmcnt(15)
	v_mfma_f32_16x16x32_bf16 v[88:91], v[232:235], v[136:139], v[88:91]
	v_add_f32_e32 v24, v24, v28
	v_add_f32_e32 v32, v32, v36
	v_mfma_f32_16x16x32_bf16 v[76:79], v[232:235], v[52:55], v[76:79]
	v_add_f32_e32 v24, v24, v32
	v_add_f32_e32 v165, v165, v24
	s_waitcnt lgkmcnt(6)
	v_mfma_f32_16x16x32_bf16 v[92:95], v[236:239], v[132:135], v[92:95]
	v_add_f32_e32 v40, v40, v41
	v_add_f32_e32 v42, v42, v43
	v_mfma_f32_16x16x32_bf16 v[80:83], v[236:239], v[140:143], v[80:83]
	v_add_f32_e32 v44, v44, v45
	v_add_f32_e32 v46, v46, v47
	s_waitcnt lgkmcnt(4)
	v_mfma_f32_16x16x32_bf16 v[92:95], v[240:243], v[136:139], v[92:95]
	v_add_f32_e32 v212, v212, v213
	v_add_f32_e32 v214, v214, v215
	v_mfma_f32_16x16x32_bf16 v[80:83], v[240:243], v[52:55], v[80:83]
	v_add_f32_e32 v216, v216, v217
	v_add_f32_e32 v218, v218, v219
	s_waitcnt lgkmcnt(2)
	v_mfma_f32_16x16x32_bf16 v[48:51], v[244:247], v[132:135], v[48:51]
	v_add_f32_e32 v40, v40, v42
	v_add_f32_e32 v44, v44, v46
	v_mfma_f32_16x16x32_bf16 v[56:59], v[244:247], v[140:143], v[56:59]
	v_add_f32_e32 v212, v212, v214
	v_add_f32_e32 v216, v216, v218
	s_waitcnt lgkmcnt(0)
	v_mfma_f32_16x16x32_bf16 v[48:51], v[220:223], v[136:139], v[48:51]
	v_add_f32_e32 v40, v40, v44
	v_add_f32_e32 v212, v212, v216
	v_mfma_f32_16x16x32_bf16 v[56:59], v[220:223], v[52:55], v[56:59]
	v_add_f32_e32 v40, v40, v212
	v_add_f32_e32 v164, v164, v40
	s_add_i32 s32, s49, 1
	s_cmp_eq_u32 s32, s9
	s_cbranch_scc1 .Lmla_mask1

; #define LAS __attribute__((address_space(3)))
; template <int DQK> __device__ __forceinline__ void stage_load(Stage<DQK>& s, const bf16* K0, int p0, const bf16* K1, int p1, const bf16* V, int pv, int tile, bool withV, int tid) {
;     { const int key = tid >> 3, c = tid & 7; s.k0 = *(const v4u*)(K0 + (size_t)(64 * tile + key) * p0 + 8 * c); }
;     if (DQK == 96) { if (tid < 256) { const int key = tid >> 2, c = tid & 3; s.k1 = *(const v4u*)(K1 + (size_t)(64 * tile + key) * p1 + 8 * c); } }
;     if (withV) { const int key = tid >> 3, c = tid & 7; s.v = *(const v4u*)(V + (size_t)(64 * tile + key) * pv + 8 * c); }
; }
; template <int DQK, int VO = KL<DQK>::VOFF> __device__ __forceinline__ void stage_store(const Stage<DQK>& s, LAS unsigned char* lds, bool withV, int tid) {
;     { const int key = tid >> 3, c = tid & 7; *(LAS v4u*)(lds + k_off<DQK>(key, c)) = s.k0; }
;     if (DQK == 96) { if (tid < 256) { const int key = tid >> 2, c = tid & 3; *(LAS v4u*)(lds + k_off<DQK>(key, 8 + c)) = s.k1; } }
;     if (withV) { const int key = tid >> 3, c = tid & 7; *(LAS v4u*)(lds + VO + (key * VSTR + 8 * c) * 2) = s.v; }
.Lmla_it2:
	s_add_i32 s96, s49, 2
	s_cmp_gt_u32 s96, s8
	s_cbranch_scc1 .Lmla_nostage2
	s_waitcnt vmcnt(0)
	ds_write_b128 v155, v[60:63] offset:26624
	ds_write_b128 v159, v[68:71] offset:26624
	s_cmp_eq_u32 s63, 0
	s_cbranch_scc1 .Lmla_nok1_12
	ds_write_b128 v157, v[64:67] offset:26624

; #define LAS __attribute__((address_space(3)))
; template <int I0, int NQ, int VO> __device__ __forceinline__ void tile_y(LAS unsigned char* lds, float (&l)[2], f32x4 (&o)[2][4], f32x4 (&s)[2][4], int fr, int fq) {
;     bf16x8 pb[NQ][2];
; #pragma unroll
;     for (int q = 0; q < NQ; ++q) {
;         f32x4 (&sq)[4] = s[I0 + q];
;         f32x2_t rs2 = {0.f, 0.f};
; #pragma unroll
;         for (int ss = 0; ss < 4; ++ss) {
; #pragma unroll
;             for (int i = 0; i < 4; ++i) sq[ss][i] = __builtin_amdgcn_exp2f(sq[ss][i]);
;             rs2 += (f32x2_t){sq[ss][0], sq[ss][1]}; rs2 += (f32x2_t){sq[ss][2], sq[ss][3]};
;         }
;         l[I0 + q] += rs2.x + rs2.y;
; #pragma unroll
;         for (int j = 0; j < 2; ++j) {
;             const v4u w = (v4u){cvtpk(sq[2 * j][0], sq[2 * j][1]), cvtpk(sq[2 * j][2], sq[2 * j][3]), cvtpk(sq[2 * j + 1][0], sq[2 * j + 1][1]), cvtpk(sq[2 * j + 1][2], sq[2 * j + 1][3])};
;             pb[q][j] = __builtin_bit_cast(bf16x8, w);
;         }
;     }
; #pragma unroll
;     for (int dt = 0; dt < 4; ++dt)
; #pragma unroll
;         for (int j = 0; j < 2; ++j) {
;             LAS unsigned char* vp = lds + VO + ((32 * j + 4 * fq + (fr >> 2)) * VSTR + 16 * dt + 4 * (fr & 3)) * 2;
;             const s16x4 lo = __builtin_bit_cast(s16x4, __builtin_amdgcn_ds_read_tr16_b64_v4i16((LAS v4i16_t*)vp));
;             const s16x4 hi = __builtin_bit_cast(s16x4, __builtin_amdgcn_ds_read_tr16_b64_v4i16((LAS v4i16_t*)(vp + 16 * VSTR * 2)));
;             const bf16x8 vf = (bf16x8){lo[0], lo[1], lo[2], lo[3], hi[0], hi[1], hi[2], hi[3]};
; #pragma unroll
; template <int DQK> __device__ __forceinline__ void x1_tile(LAS unsigned char* lds, const bf16x8 (&qf)[2][DQK / 32], const float (&m)[2], f32x4 (&s)[2][4], int fr, int fq) {
;     constexpr int NKS = DQK / 32;
; #pragma unroll
;     for (int q = 0; q < 2; ++q) { const float c = (m[q] > -1e29f) ? -m[q] : 0.f;
; #pragma unroll
;         for (int ss = 0; ss < 4; ++ss) s[q][ss] = (f32x4){c, c, c, c}; }
; #pragma unroll
;     for (int ss = 0; ss < 4; ++ss)
; #pragma unroll
;         for (int ks = 0; ks < NKS; ++ks) {
;             const bf16x8 kf = *(const LAS bf16x8*)(lds + k_off<DQK>(16 * ss + fr, 4 * ks + fq));
; #pragma unroll
;             for (int q = 0; q < 2; ++q) s[q][ss] = __builtin_amdgcn_mfma_f32_16x16x32_bf16(kf, qf[q][ks], s[q][ss], 0, 0, 0);
;         }
; }
.Lmla_nostage2:
	s_cmp_ge_u32 s49, s9
	s_cbranch_scc1 .Lmla_tail2
	ds_read_b64_tr_b16 v[220:221], v203 offset:43008
	ds_read_b64_tr_b16 v[222:223], v203 offset:45568
	ds_read_b64_tr_b16 v[224:225], v203 offset:48128
	ds_read_b64_tr_b16 v[226:227], v203 offset:50688
	ds_read_b64_tr_b16 v[228:229], v203 offset:43040
	ds_read_b64_tr_b16 v[230:231], v203 offset:45600
	ds_read_b64_tr_b16 v[232:233], v203 offset:48160
	ds_read_b64_tr_b16 v[234:235], v203 offset:50720
	ds_read_b128 v[236:239], v199
	ds_read_b128 v[240:243], v201
	ds_read_b128 v[244:247], v210
	s_waitcnt lgkmcnt(2)
	v_mfma_f32_16x16x32_bf16 v[24:27], v[236:239], v[0:3], v[204:207]
	v_exp_f32_e32 v100, v100
	v_mfma_f32_16x16x32_bf16 v[40:43], v[236:239], v[12:15], v[252:255]
	v_exp_f32_e32 v101, v101
	ds_read_b128 v[236:239], v199 offset:4096
	s_waitcnt lgkmcnt(2)
	v_mfma_f32_16x16x32_bf16 v[24:27], v[240:243], v[4:7], v[24:27]
	v_exp_f32_e32 v102, v102
	v_mfma_f32_16x16x32_bf16 v[40:43], v[240:243], v[16:19], v[40:43]
	v_exp_f32_e32 v103, v103
	ds_read_b128 v[240:243], v201 offset:4096
	s_waitcnt lgkmcnt(2)
	v_mfma_f32_16x16x32_bf16 v[24:27], v[244:247], v[8:11], v[24:27]
	v_exp_f32_e32 v104, v104
	v_mfma_f32_16x16x32_bf16 v[40:43], v[244:247], v[20:23], v[40:43]
	v_exp_f32_e32 v105, v105
	ds_read_b128 v[244:247], v210 offset:4096
	s_waitcnt lgkmcnt(2)
	v_mfma_f32_16x16x32_bf16 v[28:31], v[236:239], v[0:3], v[204:207]
	v_exp_f32_e32 v106, v106
	v_mfma_f32_16x16x32_bf16 v[44:47], v[236:239], v[12:15], v[252:255]
	v_exp_f32_e32 v107, v107
	ds_read_b128 v[236:239], v199 offset:8192
	s_waitcnt lgkmcnt(2)
	v_mfma_f32_16x16x32_bf16 v[28:31], v[240:243], v[4:7], v[28:31]
	v_exp_f32_e32 v108, v108
	v_mfma_f32_16x16x32_bf16 v[44:47], v[240:243], v[16:19], v[44:47]
	v_exp_f32_e32 v109, v109
	ds_read_b128 v[240:243], v201 offset:8192
	s_waitcnt lgkmcnt(2)
	v_mfma_f32_16x16x32_bf16 v[28:31], v[244:247], v[8:11], v[28:31]
	v_exp_f32_e32 v110, v110
	v_mfma_f32_16x16x32_bf16 v[44:47], v[244:247], v[20:23], v[44:47]
	v_exp_f32_e32 v111, v111
	ds_read_b128 v[244:247], v210 offset:8192
	s_waitcnt lgkmcnt(2)
	v_mfma_f32_16x16x32_bf16 v[32:35], v[236:239], v[0:3], v[204:207]
	v_exp_f32_e32 v112, v112
	v_mfma_f32_16x16x32_bf16 v[212:215], v[236:239], v[12:15], v[252:255]
	v_exp_f32_e32 v113, v113
	ds_read_b128 v[236:239], v199 offset:12288
	s_waitcnt lgkmcnt(2)
	v_mfma_f32_16x16x32_bf16 v[32:35], v[240:243], v[4:7], v[32:35]
	v_exp_f32_e32 v114, v114
	v_mfma_f32_16x16x32_bf16 v[212:215], v[240:243], v[16:19], v[212:215]
	v_exp_f32_e32 v115, v115
	ds_read_b128 v[240:243], v201 offset:12288
	s_waitcnt lgkmcnt(2)
	v_mfma_f32_16x16x32_bf16 v[32:35], v[244:247], v[8:11], v[32:35]
	v_cvt_pk_bf16_f32 v132, v100, v101
	v_cvt_pk_bf16_f32 v133, v102, v103
	v_mfma_f32_16x16x32_bf16 v[212:215], v[244:247], v[20:23], v[212:215]
	v_cvt_pk_bf16_f32 v134, v104, v105
	v_cvt_pk_bf16_f32 v135, v106, v107
	ds_read_b128 v[244:247], v210 offset:12288
	s_waitcnt lgkmcnt(2)
	v_mfma_f32_16x16x32_bf16 v[36:39], v[236:239], v[0:3], v[204:207]
	v_cvt_pk_bf16_f32 v136, v108, v109
	v_cvt_pk_bf16_f32 v137, v110, v111
	v_mfma_f32_16x16x32_bf16 v[216:219], v[236:239], v[12:15], v[252:255]
	v_cvt_pk_bf16_f32 v138, v112, v113
	v_cvt_pk_bf16_f32 v139, v114, v115
	ds_read_b64_tr_b16 v[236:237], v203 offset:43072
	ds_read_b64_tr_b16 v[238:239], v203 offset:45632
	s_waitcnt lgkmcnt(3)
	v_mfma_f32_16x16x32_bf16 v[36:39], v[240:243], v[4:7], v[36:39]
	v_exp_f32_e32 v116, v116
	v_mfma_f32_16x16x32_bf16 v[216:219], v[240:243], v[16:19], v[216:219]
	v_exp_f32_e32 v117, v117
	ds_read_b64_tr_b16 v[240:241], v203 offset:48192
	ds_read_b64_tr_b16 v[242:243], v203 offset:50752
	s_waitcnt lgkmcnt(4)
	v_mfma_f32_16x16x32_bf16 v[36:39], v[244:247], v[8:11], v[36:39]
	v_exp_f32_e32 v118, v118
	v_mfma_f32_16x16x32_bf16 v[216:219], v[244:247], v[20:23], v[216:219]
	v_exp_f32_e32 v119, v119
	ds_read_b64_tr_b16 v[244:245], v203 offset:43104
	ds_read_b64_tr_b16 v[246:247], v203 offset:45664
	v_exp_f32_e32 v120, v120
	v_exp_f32_e32 v121, v121
	v_exp_f32_e32 v122, v122
	v_exp_f32_e32 v123, v123
	v_exp_f32_e32 v124, v124
	v_exp_f32_e32 v125, v125
	v_exp_f32_e32 v126, v126
	v_exp_f32_e32 v127, v127
	v_exp_f32_e32 v128, v128
	v_exp_f32_e32 v129, v129
	v_exp_f32_e32 v130, v130
	v_exp_f32_e32 v131, v131
	v_cvt_pk_bf16_f32 v140, v116, v117
	v_cvt_pk_bf16_f32 v141, v118, v119
	v_cvt_pk_bf16_f32 v142, v120, v121
	v_cvt_pk_bf16_f32 v143, v122, v123
	v_cvt_pk_bf16_f32 v52, v124, v125
	v_cvt_pk_bf16_f32 v53, v126, v127
	v_cvt_pk_bf16_f32 v54, v128, v129
	v_cvt_pk_bf16_f32 v55, v130, v131
	s_waitcnt lgkmcnt(15)
	v_mfma_f32_16x16x32_bf16 v[96:99], v[220:223], v[132:135], v[96:99]
	v_add_f32_e32 v100, v100, v101
	v_add_f32_e32 v102, v102, v103
	v_mfma_f32_16x16x32_bf16 v[84:87], v[220:223], v[140:143], v[84:87]
	v_add_f32_e32 v104, v104, v105
	v_add_f32_e32 v106, v106, v107
	s_waitcnt lgkmcnt(15)
	v_mfma_f32_16x16x32_bf16 v[96:99], v[224:227], v[136:139], v[96:99]
	v_add_f32_e32 v108, v108, v109
	v_add_f32_e32 v110, v110, v111
	v_mfma_f32_16x16x32_bf16 v[84:87], v[224:227], v[52:55], v[84:87]
	v_add_f32_e32 v112, v112, v113
	v_add_f32_e32 v114, v114, v115
	ds_read_b64_tr_b16 v[220:221], v203 offset:48224
	ds_read_b64_tr_b16 v[222:223], v203 offset:50784
	s_waitcnt lgkmcnt(15)
	v_mfma_f32_16x16x32_bf16 v[88:91], v[228:231], v[132:135], v[88:91]
	v_add_f32_e32 v100, v100, v102
	v_add_f32_e32 v104, v104, v106
	v_mfma_f32_16x16x32_bf16 v[76:79], v[228:231], v[140:143], v[76:79]
	v_add_f32_e32 v108, v108, v110
	v_add_f32_e32 v112, v112, v114
	s_waitcnt lgkmcnt(15)
	v_mfma_f32_16x16x32_bf16 v[88:91], v[232:235], v[136:139], v[88:91]
	v_add_f32_e32 v100, v100, v104
	v_add_f32_e32 v108, v108, v112
	v_mfma_f32_16x16x32_bf16 v[76:79], v[232:235], v[52:55], v[76:79]
	v_add_f32_e32 v100, v100, v108
	v_add_f32_e32 v165, v165, v100
	s_waitcnt lgkmcnt(6)
	v_mfma_f32_16x16x32_bf16 v[92:95], v[236:239], v[132:135], v[92:95]
	v_add_f32_e32 v116, v116, v117
	v_add_f32_e32 v118, v118, v119
	v_mfma_f32_16x16x32_bf16 v[80:83], v[236:239], v[140:143], v[80:83]
	v_add_f32_e32 v120, v120, v121
	v_add_f32_e32 v122, v122, v123
	s_waitcnt lgkmcnt(4)
	v_mfma_f32_16x16x32_bf16 v[92:95], v[240:243], v[136:139], v[92:95]
	v_add_f32_e32 v124, v124, v125
	v_add_f32_e32 v126, v126, v127
	v_mfma_f32_16x16x32_bf16 v[80:83], v[240:243], v[52:55], v[80:83]
	v_add_f32_e32 v128, v128, v129
	v_add_f32_e32 v130, v130, v131
	s_waitcnt lgkmcnt(2)
	v_mfma_f32_16x16x32_bf16 v[48:51], v[244:247], v[132:135], v[48:51]
	v_add_f32_e32 v116, v116, v118
	v_add_f32_e32 v120, v120, v122
	v_mfma_f32_16x16x32_bf16 v[56:59], v[244:247], v[140:143], v[56:59]
	v_add_f32_e32 v124, v124, v126
	v_add_f32_e32 v128, v128, v130
	s_waitcnt lgkmcnt(0)
	v_mfma_f32_16x16x32_bf16 v[48:51], v[220:223], v[136:139], v[48:51]
	v_add_f32_e32 v116, v116, v120
	v_add_f32_e32 v124, v124, v128
	v_mfma_f32_16x16x32_bf16 v[56:59], v[220:223], v[52:55], v[56:59]
	v_add_f32_e32 v116, v116, v124
	v_add_f32_e32 v164, v164, v116
	s_add_i32 s32, s49, 1
	s_cmp_eq_u32 s32, s9
	s_cbranch_scc1 .Lmla_mask2

; #define LAS __attribute__((address_space(3)))
; template <int I0, int NQ, int VO> __device__ __forceinline__ void tile_y(LAS unsigned char* lds, float (&l)[2], f32x4 (&o)[2][4], f32x4 (&s)[2][4], int fr, int fq) {
;     bf16x8 pb[NQ][2];
; #pragma unroll
;     for (int q = 0; q < NQ; ++q) {
;         f32x4 (&sq)[4] = s[I0 + q];
;         f32x2_t rs2 = {0.f, 0.f};
; #pragma unroll
;         for (int ss = 0; ss < 4; ++ss) {
; #pragma unroll
;             for (int i = 0; i < 4; ++i) sq[ss][i] = __builtin_amdgcn_exp2f(sq[ss][i]);
;             rs2 += (f32x2_t){sq[ss][0], sq[ss][1]}; rs2 += (f32x2_t){sq[ss][2], sq[ss][3]};
;         }
;         l[I0 + q] += rs2.x + rs2.y;
; #pragma unroll
;         for (int j = 0; j < 2; ++j) {
;             const v4u w = (v4u){cvtpk(sq[2 * j][0], sq[2 * j][1]), cvtpk(sq[2 * j][2], sq[2 * j][3]), cvtpk(sq[2 * j + 1][0], sq[2 * j + 1][1]), cvtpk(sq[2 * j + 1][2], sq[2 * j + 1][3])};
;             pb[q][j] = __builtin_bit_cast(bf16x8, w);
;         }
;     }
; #pragma unroll
;     for (int dt = 0; dt < 4; ++dt)
; #pragma unroll
;         for (int j = 0; j < 2; ++j) {
;             LAS unsigned char* vp = lds + VO + ((32 * j + 4 * fq + (fr >> 2)) * VSTR + 16 * dt + 4 * (fr & 3)) * 2;
;             const s16x4 lo = __builtin_bit_cast(s16x4, __builtin_amdgcn_ds_read_tr16_b64_v4i16((LAS v4i16_t*)vp));
;             const s16x4 hi = __builtin_bit_cast(s16x4, __builtin_amdgcn_ds_read_tr16_b64_v4i16((LAS v4i16_t*)(vp + 16 * VSTR * 2)));
;             const bf16x8 vf = (bf16x8){lo[0], lo[1], lo[2], lo[3], hi[0], hi[1], hi[2], hi[3]};
; #pragma unroll
; template <int DQK> __device__ __forceinline__ void x1_tile(LAS unsigned char* lds, const bf16x8 (&qf)[2][DQK / 32], const float (&m)[2], f32x4 (&s)[2][4], int fr, int fq) {
;     constexpr int NKS = DQK / 32;
; #pragma unroll
;     for (int q = 0; q < 2; ++q) { const float c = (m[q] > -1e29f) ? -m[q] : 0.f;
; #pragma unroll
;         for (int ss = 0; ss < 4; ++ss) s[q][ss] = (f32x4){c, c, c, c}; }
; #pragma unroll
;     for (int ss = 0; ss < 4; ++ss)
; #pragma unroll
;         for (int ks = 0; ks < NKS; ++ks) {
;             const bf16x8 kf = *(const LAS bf16x8*)(lds + k_off<DQK>(16 * ss + fr, 4 * ks + fq));
; #pragma unroll
;             for (int q = 0; q < 2; ++q) s[q][ss] = __builtin_amdgcn_mfma_f32_16x16x32_bf16(kf, qf[q][ks], s[q][ss], 0, 0, 0);
;         }
; }
.Lmla_nostage3:
	s_cmp_ge_u32 s49, s9
	s_cbranch_scc1 .Lmla_tail3
	ds_read_b64_tr_b16 v[220:221], v251 offset:16384
	ds_read_b64_tr_b16 v[222:223], v251 offset:18944
	ds_read_b64_tr_b16 v[224:225], v251 offset:21504
	ds_read_b64_tr_b16 v[226:227], v251 offset:24064
	ds_read_b64_tr_b16 v[228:229], v251 offset:16416
	ds_read_b64_tr_b16 v[230:231], v251 offset:18976
	ds_read_b64_tr_b16 v[232:233], v251 offset:21536
	ds_read_b64_tr_b16 v[234:235], v251 offset:24096
	ds_read_b128 v[236:239], v195
	ds_read_b128 v[240:243], v196
	ds_read_b128 v[244:247], v202
	s_waitcnt lgkmcnt(2)
	v_mfma_f32_16x16x32_bf16 v[100:103], v[236:239], v[0:3], v[204:207]
	v_exp_f32_e32 v24, v24
	v_mfma_f32_16x16x32_bf16 v[116:119], v[236:239], v[12:15], v[252:255]
	v_exp_f32_e32 v25, v25
	ds_read_b128 v[236:239], v195 offset:4096
	s_waitcnt lgkmcnt(2)
	v_mfma_f32_16x16x32_bf16 v[100:103], v[240:243], v[4:7], v[100:103]
	v_exp_f32_e32 v26, v26
	v_mfma_f32_16x16x32_bf16 v[116:119], v[240:243], v[16:19], v[116:119]
	v_exp_f32_e32 v27, v27
	ds_read_b128 v[240:243], v196 offset:4096
	s_waitcnt lgkmcnt(2)
	v_mfma_f32_16x16x32_bf16 v[100:103], v[244:247], v[8:11], v[100:103]
	v_exp_f32_e32 v28, v28
	v_mfma_f32_16x16x32_bf16 v[116:119], v[244:247], v[20:23], v[116:119]
	v_exp_f32_e32 v29, v29
	ds_read_b128 v[244:247], v202 offset:4096
	s_waitcnt lgkmcnt(2)
	v_mfma_f32_16x16x32_bf16 v[104:107], v[236:239], v[0:3], v[204:207]
	v_exp_f32_e32 v30, v30
	v_mfma_f32_16x16x32_bf16 v[120:123], v[236:239], v[12:15], v[252:255]
	v_exp_f32_e32 v31, v31
	ds_read_b128 v[236:239], v195 offset:8192
	s_waitcnt lgkmcnt(2)
	v_mfma_f32_16x16x32_bf16 v[104:107], v[240:243], v[4:7], v[104:107]
	v_exp_f32_e32 v32, v32
	v_mfma_f32_16x16x32_bf16 v[120:123], v[240:243], v[16:19], v[120:123]
	v_exp_f32_e32 v33, v33
	ds_read_b128 v[240:243], v196 offset:8192
	s_waitcnt lgkmcnt(2)
	v_mfma_f32_16x16x32_bf16 v[104:107], v[244:247], v[8:11], v[104:107]
	v_exp_f32_e32 v34, v34
	v_mfma_f32_16x16x32_bf16 v[120:123], v[244:247], v[20:23], v[120:123]
	v_exp_f32_e32 v35, v35
	ds_read_b128 v[244:247], v202 offset:8192
	s_waitcnt lgkmcnt(2)
	v_mfma_f32_16x16x32_bf16 v[108:111], v[236:239], v[0:3], v[204:207]
	v_exp_f32_e32 v36, v36
	v_mfma_f32_16x16x32_bf16 v[124:127], v[236:239], v[12:15], v[252:255]
	v_exp_f32_e32 v37, v37
	ds_read_b128 v[236:239], v195 offset:12288
	s_waitcnt lgkmcnt(2)
	v_mfma_f32_16x16x32_bf16 v[108:111], v[240:243], v[4:7], v[108:111]
	v_exp_f32_e32 v38, v38
	v_mfma_f32_16x16x32_bf16 v[124:127], v[240:243], v[16:19], v[124:127]
	v_exp_f32_e32 v39, v39
	ds_read_b128 v[240:243], v196 offset:12288
	s_waitcnt lgkmcnt(2)
	v_mfma_f32_16x16x32_bf16 v[108:111], v[244:247], v[8:11], v[108:111]
	v_cvt_pk_bf16_f32 v132, v24, v25
	v_cvt_pk_bf16_f32 v133, v26, v27
	v_mfma_f32_16x16x32_bf16 v[124:127], v[244:247], v[20:23], v[124:127]
	v_cvt_pk_bf16_f32 v134, v28, v29
	v_cvt_pk_bf16_f32 v135, v30, v31
	ds_read_b128 v[244:247], v202 offset:12288
	s_waitcnt lgkmcnt(2)
	v_mfma_f32_16x16x32_bf16 v[112:115], v[236:239], v[0:3], v[204:207]
	v_cvt_pk_bf16_f32 v136, v32, v33
	v_cvt_pk_bf16_f32 v137, v34, v35
	v_mfma_f32_16x16x32_bf16 v[128:131], v[236:239], v[12:15], v[252:255]
	v_cvt_pk_bf16_f32 v138, v36, v37
	v_cvt_pk_bf16_f32 v139, v38, v39
	ds_read_b64_tr_b16 v[236:237], v251 offset:16448
	ds_read_b64_tr_b16 v[238:239], v251 offset:19008
	s_waitcnt lgkmcnt(3)
	v_mfma_f32_16x16x32_bf16 v[112:115], v[240:243], v[4:7], v[112:115]
	v_exp_f32_e32 v40, v40
	v_mfma_f32_16x16x32_bf16 v[128:131], v[240:243], v[16:19], v[128:131]
	v_exp_f32_e32 v41, v41
	ds_read_b64_tr_b16 v[240:241], v251 offset:21568
	ds_read_b64_tr_b16 v[242:243], v251 offset:24128
	s_waitcnt lgkmcnt(4)
	v_mfma_f32_16x16x32_bf16 v[112:115], v[244:247], v[8:11], v[112:115]
	v_exp_f32_e32 v42, v42
	v_mfma_f32_16x16x32_bf16 v[128:131], v[244:247], v[20:23], v[128:131]
	v_exp_f32_e32 v43, v43
	ds_read_b64_tr_b16 v[244:245], v251 offset:16480
	ds_read_b64_tr_b16 v[246:247], v251 offset:19040
	v_exp_f32_e32 v44, v44
	v_exp_f32_e32 v45, v45
	v_exp_f32_e32 v46, v46
	v_exp_f32_e32 v47, v47
	v_exp_f32_e32 v212, v212
	v_exp_f32_e32 v213, v213
	v_exp_f32_e32 v214, v214
	v_exp_f32_e32 v215, v215
	v_exp_f32_e32 v216, v216
	v_exp_f32_e32 v217, v217
	v_exp_f32_e32 v218, v218
	v_exp_f32_e32 v219, v219
	v_cvt_pk_bf16_f32 v140, v40, v41
	v_cvt_pk_bf16_f32 v141, v42, v43
	v_cvt_pk_bf16_f32 v142, v44, v45
	v_cvt_pk_bf16_f32 v143, v46, v47
	v_cvt_pk_bf16_f32 v52, v212, v213
	v_cvt_pk_bf16_f32 v53, v214, v215
	v_cvt_pk_bf16_f32 v54, v216, v217
	v_cvt_pk_bf16_f32 v55, v218, v219
	s_waitcnt lgkmcnt(15)
	v_mfma_f32_16x16x32_bf16 v[96:99], v[220:223], v[132:135], v[96:99]
	v_add_f32_e32 v24, v24, v25
	v_add_f32_e32 v26, v26, v27
	v_mfma_f32_16x16x32_bf16 v[84:87], v[220:223], v[140:143], v[84:87]
	v_add_f32_e32 v28, v28, v29
	v_add_f32_e32 v30, v30, v31
	s_waitcnt lgkmcnt(15)
	v_mfma_f32_16x16x32_bf16 v[96:99], v[224:227], v[136:139], v[96:99]
	v_add_f32_e32 v32, v32, v33
	v_add_f32_e32 v34, v34, v35
	v_mfma_f32_16x16x32_bf16 v[84:87], v[224:227], v[52:55], v[84:87]
	v_add_f32_e32 v36, v36, v37
	v_add_f32_e32 v38, v38, v39
	ds_read_b64_tr_b16 v[220:221], v251 offset:21600
	ds_read_b64_tr_b16 v[222:223], v251 offset:24160
	s_waitcnt lgkmcnt(15)
	v_mfma_f32_16x16x32_bf16 v[88:91], v[228:231], v[132:135], v[88:91]
	v_add_f32_e32 v24, v24, v26
	v_add_f32_e32 v28, v28, v30
	v_mfma_f32_16x16x32_bf16 v[76:79], v[228:231], v[140:143], v[76:79]
	v_add_f32_e32 v32, v32, v34
	v_add_f32_e32 v36, v36, v38
	s_waitcnt lgkmcnt(15)
	v_mfma_f32_16x16x32_bf16 v[88:91], v[232:235], v[136:139], v[88:91]
	v_add_f32_e32 v24, v24, v28
	v_add_f32_e32 v32, v32, v36
	v_mfma_f32_16x16x32_bf16 v[76:79], v[232:235], v[52:55], v[76:79]
	v_add_f32_e32 v24, v24, v32
	v_add_f32_e32 v165, v165, v24
	s_waitcnt lgkmcnt(6)
	v_mfma_f32_16x16x32_bf16 v[92:95], v[236:239], v[132:135], v[92:95]
	v_add_f32_e32 v40, v40, v41
	v_add_f32_e32 v42, v42, v43
	v_mfma_f32_16x16x32_bf16 v[80:83], v[236:239], v[140:143], v[80:83]
	v_add_f32_e32 v44, v44, v45
	v_add_f32_e32 v46, v46, v47
	s_waitcnt lgkmcnt(4)
	v_mfma_f32_16x16x32_bf16 v[92:95], v[240:243], v[136:139], v[92:95]
	v_add_f32_e32 v212, v212, v213
	v_add_f32_e32 v214, v214, v215
	v_mfma_f32_16x16x32_bf16 v[80:83], v[240:243], v[52:55], v[80:83]
	v_add_f32_e32 v216, v216, v217
	v_add_f32_e32 v218, v218, v219
	s_waitcnt lgkmcnt(2)
	v_mfma_f32_16x16x32_bf16 v[48:51], v[244:247], v[132:135], v[48:51]
	v_add_f32_e32 v40, v40, v42
	v_add_f32_e32 v44, v44, v46
	v_mfma_f32_16x16x32_bf16 v[56:59], v[244:247], v[140:143], v[56:59]
	v_add_f32_e32 v212, v212, v214
	v_add_f32_e32 v216, v216, v218
	s_waitcnt lgkmcnt(0)
	v_mfma_f32_16x16x32_bf16 v[48:51], v[220:223], v[136:139], v[48:51]
	v_add_f32_e32 v40, v40, v44
	v_add_f32_e32 v212, v212, v216
	v_mfma_f32_16x16x32_bf16 v[56:59], v[220:223], v[52:55], v[56:59]
	v_add_f32_e32 v40, v40, v212
	v_add_f32_e32 v164, v164, v40
	s_add_i32 s32, s49, 1
	s_cmp_eq_u32 s32, s9
	s_cbranch_scc1 .Lmla_mask3

.Lmla_nostage4:
	s_cmp_ge_u32 s49, s9
	s_cbranch_scc1 .Lmla_tail4
; #define LAS __attribute__((address_space(3)))
; template <int I0, int NQ, int VO> __device__ __forceinline__ void tile_y(LAS unsigned char* lds, float (&l)[2], f32x4 (&o)[2][4], f32x4 (&s)[2][4], int fr, int fq) {
;     bf16x8 pb[NQ][2];
; #pragma unroll
;     for (int q = 0; q < NQ; ++q) {
;         f32x4 (&sq)[4] = s[I0 + q];
;         f32x2_t rs2 = {0.f, 0.f};
; #pragma unroll
;         for (int ss = 0; ss < 4; ++ss) {
; #pragma unroll
;             for (int i = 0; i < 4; ++i) sq[ss][i] = __builtin_amdgcn_exp2f(sq[ss][i]);
;             rs2 += (f32x2_t){sq[ss][0], sq[ss][1]}; rs2 += (f32x2_t){sq[ss][2], sq[ss][3]};
;         }
;         l[I0 + q] += rs2.x + rs2.y;
; #pragma unroll
;         for (int j = 0; j < 2; ++j) {
;             const v4u w = (v4u){cvtpk(sq[2 * j][0], sq[2 * j][1]), cvtpk(sq[2 * j][2], sq[2 * j][3]), cvtpk(sq[2 * j + 1][0], sq[2 * j + 1][1]), cvtpk(sq[2 * j + 1][2], sq[2 * j + 1][3])};
;             pb[q][j] = __builtin_bit_cast(bf16x8, w);
;         }
;     }
; #pragma unroll
;     for (int dt = 0; dt < 4; ++dt)
; #pragma unroll
;         for (int j = 0; j < 2; ++j) {
;             LAS unsigned char* vp = lds + VO + ((32 * j + 4 * fq + (fr >> 2)) * VSTR + 16 * dt + 4 * (fr & 3)) * 2;
;             const s16x4 lo = __builtin_bit_cast(s16x4, __builtin_amdgcn_ds_read_tr16_b64_v4i16((LAS v4i16_t*)vp));
;             const s16x4 hi = __builtin_bit_cast(s16x4, __builtin_amdgcn_ds_read_tr16_b64_v4i16((LAS v4i16_t*)(vp + 16 * VSTR * 2)));
;             const bf16x8 vf = (bf16x8){lo[0], lo[1], lo[2], lo[3], hi[0], hi[1], hi[2], hi[3]};
; #pragma unroll
; template <int DQK> __device__ __forceinline__ void x1_tile(LAS unsigned char* lds, const bf16x8 (&qf)[2][DQK / 32], const float (&m)[2], f32x4 (&s)[2][4], int fr, int fq) {
;     constexpr int NKS = DQK / 32;
; #pragma unroll
;     for (int q = 0; q < 2; ++q) { const float c = (m[q] > -1e29f) ? -m[q] : 0.f;
; #pragma unroll
;         for (int ss = 0; ss < 4; ++ss) s[q][ss] = (f32x4){c, c, c, c}; }
; #pragma unroll
;     for (int ss = 0; ss < 4; ++ss)
; #pragma unroll
;         for (int ks = 0; ks < NKS; ++ks) {
;             const bf16x8 kf = *(const LAS bf16x8*)(lds + k_off<DQK>(16 * ss + fr, 4 * ks + fq));
; #pragma unroll
;             for (int q = 0; q < 2; ++q) s[q][ss] = __builtin_amdgcn_mfma_f32_16x16x32_bf16(kf, qf[q][ks], s[q][ss], 0, 0, 0);
;         }
; }
	ds_read_b64_tr_b16 v[220:221], v203 offset:16384
	ds_read_b64_tr_b16 v[222:223], v203 offset:18944
	ds_read_b64_tr_b16 v[224:225], v203 offset:21504
	ds_read_b64_tr_b16 v[226:227], v203 offset:24064
	ds_read_b64_tr_b16 v[228:229], v203 offset:16416
	ds_read_b64_tr_b16 v[230:231], v203 offset:18976
	ds_read_b64_tr_b16 v[232:233], v203 offset:21536
	ds_read_b64_tr_b16 v[234:235], v203 offset:24096
	ds_read_b128 v[236:239], v195 offset:26624
	ds_read_b128 v[240:243], v196 offset:26624
	ds_read_b128 v[244:247], v202 offset:26624
	s_waitcnt lgkmcnt(2)
	v_mfma_f32_16x16x32_bf16 v[24:27], v[236:239], v[0:3], v[204:207]
	v_exp_f32_e32 v100, v100
	v_mfma_f32_16x16x32_bf16 v[40:43], v[236:239], v[12:15], v[252:255]
	v_exp_f32_e32 v101, v101
	ds_read_b128 v[236:239], v195 offset:30720
	s_waitcnt lgkmcnt(2)
	v_mfma_f32_16x16x32_bf16 v[24:27], v[240:243], v[4:7], v[24:27]
	v_exp_f32_e32 v102, v102
	v_mfma_f32_16x16x32_bf16 v[40:43], v[240:243], v[16:19], v[40:43]
	v_exp_f32_e32 v103, v103
	ds_read_b128 v[240:243], v196 offset:30720
	s_waitcnt lgkmcnt(2)
	v_mfma_f32_16x16x32_bf16 v[24:27], v[244:247], v[8:11], v[24:27]
	v_exp_f32_e32 v104, v104
	v_mfma_f32_16x16x32_bf16 v[40:43], v[244:247], v[20:23], v[40:43]
	v_exp_f32_e32 v105, v105
	ds_read_b128 v[244:247], v202 offset:30720
	s_waitcnt lgkmcnt(2)
	v_mfma_f32_16x16x32_bf16 v[28:31], v[236:239], v[0:3], v[204:207]
	v_exp_f32_e32 v106, v106
	v_mfma_f32_16x16x32_bf16 v[44:47], v[236:239], v[12:15], v[252:255]
	v_exp_f32_e32 v107, v107
	ds_read_b128 v[236:239], v195 offset:34816
	s_waitcnt lgkmcnt(2)
	v_mfma_f32_16x16x32_bf16 v[28:31], v[240:243], v[4:7], v[28:31]
	v_exp_f32_e32 v108, v108
	v_mfma_f32_16x16x32_bf16 v[44:47], v[240:243], v[16:19], v[44:47]
	v_exp_f32_e32 v109, v109
	ds_read_b128 v[240:243], v196 offset:34816
	s_waitcnt lgkmcnt(2)
	v_mfma_f32_16x16x32_bf16 v[28:31], v[244:247], v[8:11], v[28:31]
	v_exp_f32_e32 v110, v110
	v_mfma_f32_16x16x32_bf16 v[44:47], v[244:247], v[20:23], v[44:47]
	v_exp_f32_e32 v111, v111
	ds_read_b128 v[244:247], v202 offset:34816
	s_waitcnt lgkmcnt(2)
	v_mfma_f32_16x16x32_bf16 v[32:35], v[236:239], v[0:3], v[204:207]
	v_exp_f32_e32 v112, v112
	v_mfma_f32_16x16x32_bf16 v[212:215], v[236:239], v[12:15], v[252:255]
	v_exp_f32_e32 v113, v113
	ds_read_b128 v[236:239], v195 offset:38912
	s_waitcnt lgkmcnt(2)
	v_mfma_f32_16x16x32_bf16 v[32:35], v[240:243], v[4:7], v[32:35]
	v_exp_f32_e32 v114, v114
	v_mfma_f32_16x16x32_bf16 v[212:215], v[240:243], v[16:19], v[212:215]
	v_exp_f32_e32 v115, v115
	ds_read_b128 v[240:243], v196 offset:38912
	s_waitcnt lgkmcnt(2)
	v_mfma_f32_16x16x32_bf16 v[32:35], v[244:247], v[8:11], v[32:35]
	v_cvt_pk_bf16_f32 v132, v100, v101
	v_cvt_pk_bf16_f32 v133, v102, v103
	v_mfma_f32_16x16x32_bf16 v[212:215], v[244:247], v[20:23], v[212:215]
	v_cvt_pk_bf16_f32 v134, v104, v105
	v_cvt_pk_bf16_f32 v135, v106, v107
	ds_read_b128 v[244:247], v202 offset:38912
	s_waitcnt lgkmcnt(2)
	v_mfma_f32_16x16x32_bf16 v[36:39], v[236:239], v[0:3], v[204:207]
	v_cvt_pk_bf16_f32 v136, v108, v109
	v_cvt_pk_bf16_f32 v137, v110, v111
	v_mfma_f32_16x16x32_bf16 v[216:219], v[236:239], v[12:15], v[252:255]
	v_cvt_pk_bf16_f32 v138, v112, v113
	v_cvt_pk_bf16_f32 v139, v114, v115
	ds_read_b64_tr_b16 v[236:237], v203 offset:16448
	ds_read_b64_tr_b16 v[238:239], v203 offset:19008
	s_waitcnt lgkmcnt(3)
	v_mfma_f32_16x16x32_bf16 v[36:39], v[240:243], v[4:7], v[36:39]
	v_exp_f32_e32 v116, v116
	v_mfma_f32_16x16x32_bf16 v[216:219], v[240:243], v[16:19], v[216:219]
	v_exp_f32_e32 v117, v117
	ds_read_b64_tr_b16 v[240:241], v203 offset:21568
	ds_read_b64_tr_b16 v[242:243], v203 offset:24128
	s_waitcnt lgkmcnt(4)
	v_mfma_f32_16x16x32_bf16 v[36:39], v[244:247], v[8:11], v[36:39]
	v_exp_f32_e32 v118, v118
	v_mfma_f32_16x16x32_bf16 v[216:219], v[244:247], v[20:23], v[216:219]
	v_exp_f32_e32 v119, v119
	ds_read_b64_tr_b16 v[244:245], v203 offset:16480
	ds_read_b64_tr_b16 v[246:247], v203 offset:19040
	v_exp_f32_e32 v120, v120
	v_exp_f32_e32 v121, v121
	v_exp_f32_e32 v122, v122
	v_exp_f32_e32 v123, v123
	v_exp_f32_e32 v124, v124
	v_exp_f32_e32 v125, v125
	v_exp_f32_e32 v126, v126
	v_exp_f32_e32 v127, v127
	v_exp_f32_e32 v128, v128
	v_exp_f32_e32 v129, v129
	v_exp_f32_e32 v130, v130
	v_exp_f32_e32 v131, v131
	v_cvt_pk_bf16_f32 v140, v116, v117
	v_cvt_pk_bf16_f32 v141, v118, v119
	v_cvt_pk_bf16_f32 v142, v120, v121
	v_cvt_pk_bf16_f32 v143, v122, v123
	v_cvt_pk_bf16_f32 v52, v124, v125
	v_cvt_pk_bf16_f32 v53, v126, v127
	v_cvt_pk_bf16_f32 v54, v128, v129
	v_cvt_pk_bf16_f32 v55, v130, v131
	s_waitcnt lgkmcnt(15)
	v_mfma_f32_16x16x32_bf16 v[96:99], v[220:223], v[132:135], v[96:99]
	v_add_f32_e32 v100, v100, v101
	v_add_f32_e32 v102, v102, v103
	v_mfma_f32_16x16x32_bf16 v[84:87], v[220:223], v[140:143], v[84:87]
	v_add_f32_e32 v104, v104, v105
	v_add_f32_e32 v106, v106, v107
	s_waitcnt lgkmcnt(15)
	v_mfma_f32_16x16x32_bf16 v[96:99], v[224:227], v[136:139], v[96:99]
	v_add_f32_e32 v108, v108, v109
	v_add_f32_e32 v110, v110, v111
	v_mfma_f32_16x16x32_bf16 v[84:87], v[224:227], v[52:55], v[84:87]
	v_add_f32_e32 v112, v112, v113
	v_add_f32_e32 v114, v114, v115
	ds_read_b64_tr_b16 v[220:221], v203 offset:21600
	ds_read_b64_tr_b16 v[222:223], v203 offset:24160
	s_waitcnt lgkmcnt(15)
	v_mfma_f32_16x16x32_bf16 v[88:91], v[228:231], v[132:135], v[88:91]
	v_add_f32_e32 v100, v100, v102
	v_add_f32_e32 v104, v104, v106
	v_mfma_f32_16x16x32_bf16 v[76:79], v[228:231], v[140:143], v[76:79]
	v_add_f32_e32 v108, v108, v110
	v_add_f32_e32 v112, v112, v114
	s_waitcnt lgkmcnt(15)
	v_mfma_f32_16x16x32_bf16 v[88:91], v[232:235], v[136:139], v[88:91]
	v_add_f32_e32 v100, v100, v104
	v_add_f32_e32 v108, v108, v112
	v_mfma_f32_16x16x32_bf16 v[76:79], v[232:235], v[52:55], v[76:79]
	v_add_f32_e32 v100, v100, v108
	v_add_f32_e32 v165, v165, v100
	s_waitcnt lgkmcnt(6)
	v_mfma_f32_16x16x32_bf16 v[92:95], v[236:239], v[132:135], v[92:95]
	v_add_f32_e32 v116, v116, v117
	v_add_f32_e32 v118, v118, v119
	v_mfma_f32_16x16x32_bf16 v[80:83], v[236:239], v[140:143], v[80:83]
	v_add_f32_e32 v120, v120, v121
	v_add_f32_e32 v122, v122, v123
	s_waitcnt lgkmcnt(4)
	v_mfma_f32_16x16x32_bf16 v[92:95], v[240:243], v[136:139], v[92:95]
	v_add_f32_e32 v124, v124, v125
	v_add_f32_e32 v126, v126, v127
	v_mfma_f32_16x16x32_bf16 v[80:83], v[240:243], v[52:55], v[80:83]
	v_add_f32_e32 v128, v128, v129
	v_add_f32_e32 v130, v130, v131
	s_waitcnt lgkmcnt(2)
	v_mfma_f32_16x16x32_bf16 v[48:51], v[244:247], v[132:135], v[48:51]
	v_add_f32_e32 v116, v116, v118
	v_add_f32_e32 v120, v120, v122
	v_mfma_f32_16x16x32_bf16 v[56:59], v[244:247], v[140:143], v[56:59]
	v_add_f32_e32 v124, v124, v126
	v_add_f32_e32 v128, v128, v130
	s_waitcnt lgkmcnt(0)
	v_mfma_f32_16x16x32_bf16 v[48:51], v[220:223], v[136:139], v[48:51]
	v_add_f32_e32 v116, v116, v120
	v_add_f32_e32 v124, v124, v128
	v_mfma_f32_16x16x32_bf16 v[56:59], v[220:223], v[52:55], v[56:59]
	v_add_f32_e32 v116, v116, v124
	v_add_f32_e32 v164, v164, v116
	s_add_i32 s32, s49, 1
	s_cmp_eq_u32 s32, s9
	s_cbranch_scc1 .Lmla_mask4

; #define LAS __attribute__((address_space(3)))
; template <int I0, int NQ, int VO> __device__ __forceinline__ void tile_y(LAS unsigned char* lds, float (&l)[2], f32x4 (&o)[2][4], f32x4 (&s)[2][4], int fr, int fq) {
;     bf16x8 pb[NQ][2];
; #pragma unroll
;     for (int q = 0; q < NQ; ++q) {
;         f32x4 (&sq)[4] = s[I0 + q];
;         f32x2_t rs2 = {0.f, 0.f};
; #pragma unroll
;         for (int ss = 0; ss < 4; ++ss) {
; #pragma unroll
;             for (int i = 0; i < 4; ++i) sq[ss][i] = __builtin_amdgcn_exp2f(sq[ss][i]);
;             rs2 += (f32x2_t){sq[ss][0], sq[ss][1]}; rs2 += (f32x2_t){sq[ss][2], sq[ss][3]};
;         }
;         l[I0 + q] += rs2.x + rs2.y;
; #pragma unroll
;         for (int j = 0; j < 2; ++j) {
;             const v4u w = (v4u){cvtpk(sq[2 * j][0], sq[2 * j][1]), cvtpk(sq[2 * j][2], sq[2 * j][3]), cvtpk(sq[2 * j + 1][0], sq[2 * j + 1][1]), cvtpk(sq[2 * j + 1][2], sq[2 * j + 1][3])};
;             pb[q][j] = __builtin_bit_cast(bf16x8, w);
;         }
;     }
; #pragma unroll
;     for (int dt = 0; dt < 4; ++dt)
; #pragma unroll
;         for (int j = 0; j < 2; ++j) {
;             LAS unsigned char* vp = lds + VO + ((32 * j + 4 * fq + (fr >> 2)) * VSTR + 16 * dt + 4 * (fr & 3)) * 2;
;             const s16x4 lo = __builtin_bit_cast(s16x4, __builtin_amdgcn_ds_read_tr16_b64_v4i16((LAS v4i16_t*)vp));
;             const s16x4 hi = __builtin_bit_cast(s16x4, __builtin_amdgcn_ds_read_tr16_b64_v4i16((LAS v4i16_t*)(vp + 16 * VSTR * 2)));
;             const bf16x8 vf = (bf16x8){lo[0], lo[1], lo[2], lo[3], hi[0], hi[1], hi[2], hi[3]};
; #pragma unroll
; template <int DQK> __device__ __forceinline__ void x1_tile(LAS unsigned char* lds, const bf16x8 (&qf)[2][DQK / 32], const float (&m)[2], f32x4 (&s)[2][4], int fr, int fq) {
;     constexpr int NKS = DQK / 32;
; #pragma unroll
;     for (int q = 0; q < 2; ++q) { const float c = (m[q] > -1e29f) ? -m[q] : 0.f;
; #pragma unroll
;         for (int ss = 0; ss < 4; ++ss) s[q][ss] = (f32x4){c, c, c, c}; }
; #pragma unroll
;     for (int ss = 0; ss < 4; ++ss)
; #pragma unroll
;         for (int ks = 0; ks < NKS; ++ks) {
;             const bf16x8 kf = *(const LAS bf16x8*)(lds + k_off<DQK>(16 * ss + fr, 4 * ks + fq));
; #pragma unroll
;             for (int q = 0; q < 2; ++q) s[q][ss] = __builtin_amdgcn_mfma_f32_16x16x32_bf16(kf, qf[q][ks], s[q][ss], 0, 0, 0);
;         }
; }
.Lmla_nostage5:
	s_cmp_ge_u32 s49, s9
	s_cbranch_scc1 .Lmla_tail5
	ds_read_b64_tr_b16 v[220:221], v203 offset:43008
	ds_read_b64_tr_b16 v[222:223], v203 offset:45568
	ds_read_b64_tr_b16 v[224:225], v203 offset:48128
	ds_read_b64_tr_b16 v[226:227], v203 offset:50688
	ds_read_b64_tr_b16 v[228:229], v203 offset:43040
	ds_read_b64_tr_b16 v[230:231], v203 offset:45600
	ds_read_b64_tr_b16 v[232:233], v203 offset:48160
	ds_read_b64_tr_b16 v[234:235], v203 offset:50720
	ds_read_b128 v[236:239], v199
	ds_read_b128 v[240:243], v201
	ds_read_b128 v[244:247], v210
	s_waitcnt lgkmcnt(2)
	v_mfma_f32_16x16x32_bf16 v[100:103], v[236:239], v[0:3], v[204:207]
	v_exp_f32_e32 v24, v24
	v_mfma_f32_16x16x32_bf16 v[116:119], v[236:239], v[12:15], v[252:255]
	v_exp_f32_e32 v25, v25
	ds_read_b128 v[236:239], v199 offset:4096
	s_waitcnt lgkmcnt(2)
	v_mfma_f32_16x16x32_bf16 v[100:103], v[240:243], v[4:7], v[100:103]
	v_exp_f32_e32 v26, v26
	v_mfma_f32_16x16x32_bf16 v[116:119], v[240:243], v[16:19], v[116:119]
	v_exp_f32_e32 v27, v27
	ds_read_b128 v[240:243], v201 offset:4096
	s_waitcnt lgkmcnt(2)
	v_mfma_f32_16x16x32_bf16 v[100:103], v[244:247], v[8:11], v[100:103]
	v_exp_f32_e32 v28, v28
	v_mfma_f32_16x16x32_bf16 v[116:119], v[244:247], v[20:23], v[116:119]
	v_exp_f32_e32 v29, v29
	ds_read_b128 v[244:247], v210 offset:4096
	s_waitcnt lgkmcnt(2)
	v_mfma_f32_16x16x32_bf16 v[104:107], v[236:239], v[0:3], v[204:207]
	v_exp_f32_e32 v30, v30
	v_mfma_f32_16x16x32_bf16 v[120:123], v[236:239], v[12:15], v[252:255]
	v_exp_f32_e32 v31, v31
	ds_read_b128 v[236:239], v199 offset:8192
	s_waitcnt lgkmcnt(2)
	v_mfma_f32_16x16x32_bf16 v[104:107], v[240:243], v[4:7], v[104:107]
	v_exp_f32_e32 v32, v32
	v_mfma_f32_16x16x32_bf16 v[120:123], v[240:243], v[16:19], v[120:123]
	v_exp_f32_e32 v33, v33
	ds_read_b128 v[240:243], v201 offset:8192
	s_waitcnt lgkmcnt(2)
	v_mfma_f32_16x16x32_bf16 v[104:107], v[244:247], v[8:11], v[104:107]
	v_exp_f32_e32 v34, v34
	v_mfma_f32_16x16x32_bf16 v[120:123], v[244:247], v[20:23], v[120:123]
	v_exp_f32_e32 v35, v35
	ds_read_b128 v[244:247], v210 offset:8192
	s_waitcnt lgkmcnt(2)
	v_mfma_f32_16x16x32_bf16 v[108:111], v[236:239], v[0:3], v[204:207]
	v_exp_f32_e32 v36, v36
	v_mfma_f32_16x16x32_bf16 v[124:127], v[236:239], v[12:15], v[252:255]
	v_exp_f32_e32 v37, v37
	ds_read_b128 v[236:239], v199 offset:12288
	s_waitcnt lgkmcnt(2)
	v_mfma_f32_16x16x32_bf16 v[108:111], v[240:243], v[4:7], v[108:111]
	v_exp_f32_e32 v38, v38
	v_mfma_f32_16x16x32_bf16 v[124:127], v[240:243], v[16:19], v[124:127]
	v_exp_f32_e32 v39, v39
	ds_read_b128 v[240:243], v201 offset:12288
	s_waitcnt lgkmcnt(2)
	v_mfma_f32_16x16x32_bf16 v[108:111], v[244:247], v[8:11], v[108:111]
	v_cvt_pk_bf16_f32 v132, v24, v25
	v_cvt_pk_bf16_f32 v133, v26, v27
	v_mfma_f32_16x16x32_bf16 v[124:127], v[244:247], v[20:23], v[124:127]
	v_cvt_pk_bf16_f32 v134, v28, v29
	v_cvt_pk_bf16_f32 v135, v30, v31
	ds_read_b128 v[244:247], v210 offset:12288
	s_waitcnt lgkmcnt(2)
	v_mfma_f32_16x16x32_bf16 v[112:115], v[236:239], v[0:3], v[204:207]
	v_cvt_pk_bf16_f32 v136, v32, v33
	v_cvt_pk_bf16_f32 v137, v34, v35
	v_mfma_f32_16x16x32_bf16 v[128:131], v[236:239], v[12:15], v[252:255]
	v_cvt_pk_bf16_f32 v138, v36, v37
	v_cvt_pk_bf16_f32 v139, v38, v39
	ds_read_b64_tr_b16 v[236:237], v203 offset:43072
	ds_read_b64_tr_b16 v[238:239], v203 offset:45632
	s_waitcnt lgkmcnt(3)
	v_mfma_f32_16x16x32_bf16 v[112:115], v[240:243], v[4:7], v[112:115]
	v_exp_f32_e32 v40, v40
	v_mfma_f32_16x16x32_bf16 v[128:131], v[240:243], v[16:19], v[128:131]
	v_exp_f32_e32 v41, v41
	ds_read_b64_tr_b16 v[240:241], v203 offset:48192
	ds_read_b64_tr_b16 v[242:243], v203 offset:50752
	s_waitcnt lgkmcnt(4)
	v_mfma_f32_16x16x32_bf16 v[112:115], v[244:247], v[8:11], v[112:115]
	v_exp_f32_e32 v42, v42
	v_mfma_f32_16x16x32_bf16 v[128:131], v[244:247], v[20:23], v[128:131]
	v_exp_f32_e32 v43, v43
	ds_read_b64_tr_b16 v[244:245], v203 offset:43104
	ds_read_b64_tr_b16 v[246:247], v203 offset:45664
	v_exp_f32_e32 v44, v44
	v_exp_f32_e32 v45, v45
	v_exp_f32_e32 v46, v46
	v_exp_f32_e32 v47, v47
	v_exp_f32_e32 v212, v212
	v_exp_f32_e32 v213, v213
	v_exp_f32_e32 v214, v214
	v_exp_f32_e32 v215, v215
	v_exp_f32_e32 v216, v216
	v_exp_f32_e32 v217, v217
	v_exp_f32_e32 v218, v218
	v_exp_f32_e32 v219, v219
	v_cvt_pk_bf16_f32 v140, v40, v41
	v_cvt_pk_bf16_f32 v141, v42, v43
	v_cvt_pk_bf16_f32 v142, v44, v45
	v_cvt_pk_bf16_f32 v143, v46, v47
	v_cvt_pk_bf16_f32 v52, v212, v213
	v_cvt_pk_bf16_f32 v53, v214, v215
	v_cvt_pk_bf16_f32 v54, v216, v217
	v_cvt_pk_bf16_f32 v55, v218, v219
	s_waitcnt lgkmcnt(15)
	v_mfma_f32_16x16x32_bf16 v[96:99], v[220:223], v[132:135], v[96:99]
	v_add_f32_e32 v24, v24, v25
	v_add_f32_e32 v26, v26, v27
	v_mfma_f32_16x16x32_bf16 v[84:87], v[220:223], v[140:143], v[84:87]
	v_add_f32_e32 v28, v28, v29
	v_add_f32_e32 v30, v30, v31
	s_waitcnt lgkmcnt(15)
	v_mfma_f32_16x16x32_bf16 v[96:99], v[224:227], v[136:139], v[96:99]
	v_add_f32_e32 v32, v32, v33
	v_add_f32_e32 v34, v34, v35
	v_mfma_f32_16x16x32_bf16 v[84:87], v[224:227], v[52:55], v[84:87]
	v_add_f32_e32 v36, v36, v37
	v_add_f32_e32 v38, v38, v39
	ds_read_b64_tr_b16 v[220:221], v203 offset:48224
	ds_read_b64_tr_b16 v[222:223], v203 offset:50784
	s_waitcnt lgkmcnt(15)
	v_mfma_f32_16x16x32_bf16 v[88:91], v[228:231], v[132:135], v[88:91]
	v_add_f32_e32 v24, v24, v26
	v_add_f32_e32 v28, v28, v30
	v_mfma_f32_16x16x32_bf16 v[76:79], v[228:231], v[140:143], v[76:79]
	v_add_f32_e32 v32, v32, v34
	v_add_f32_e32 v36, v36, v38
	s_waitcnt lgkmcnt(15)
	v_mfma_f32_16x16x32_bf16 v[88:91], v[232:235], v[136:139], v[88:91]
	v_add_f32_e32 v24, v24, v28
	v_add_f32_e32 v32, v32, v36
	v_mfma_f32_16x16x32_bf16 v[76:79], v[232:235], v[52:55], v[76:79]
	v_add_f32_e32 v24, v24, v32
	v_add_f32_e32 v165, v165, v24
	s_waitcnt lgkmcnt(6)
	v_mfma_f32_16x16x32_bf16 v[92:95], v[236:239], v[132:135], v[92:95]
	v_add_f32_e32 v40, v40, v41
	v_add_f32_e32 v42, v42, v43
	v_mfma_f32_16x16x32_bf16 v[80:83], v[236:239], v[140:143], v[80:83]
	v_add_f32_e32 v44, v44, v45
	v_add_f32_e32 v46, v46, v47
	s_waitcnt lgkmcnt(4)
	v_mfma_f32_16x16x32_bf16 v[92:95], v[240:243], v[136:139], v[92:95]
	v_add_f32_e32 v212, v212, v213
	v_add_f32_e32 v214, v214, v215
	v_mfma_f32_16x16x32_bf16 v[80:83], v[240:243], v[52:55], v[80:83]
	v_add_f32_e32 v216, v216, v217
	v_add_f32_e32 v218, v218, v219
	s_waitcnt lgkmcnt(2)
	v_mfma_f32_16x16x32_bf16 v[48:51], v[244:247], v[132:135], v[48:51]
	v_add_f32_e32 v40, v40, v42
	v_add_f32_e32 v44, v44, v46
	v_mfma_f32_16x16x32_bf16 v[56:59], v[244:247], v[140:143], v[56:59]
	v_add_f32_e32 v212, v212, v214
	v_add_f32_e32 v216, v216, v218
	s_waitcnt lgkmcnt(0)
	v_mfma_f32_16x16x32_bf16 v[48:51], v[220:223], v[136:139], v[48:51]
	v_add_f32_e32 v40, v40, v44
	v_add_f32_e32 v212, v212, v216
	v_mfma_f32_16x16x32_bf16 v[56:59], v[220:223], v[52:55], v[56:59]
	v_add_f32_e32 v40, v40, v212
	v_add_f32_e32 v164, v164, v40
	s_add_i32 s32, s49, 1
	s_cmp_eq_u32 s32, s9
	s_cbranch_scc1 .Lmla_mask5

; #define LAS __attribute__((address_space(3)))
; __device__ __forceinline__ unsigned cvtpk(float lo, float hi) { f32x2_t v = {lo, hi}; bf16x2_t b = __builtin_convertvector(v, bf16x2_t); return __builtin_bit_cast(unsigned, b); }
; template <int I0, int NQ, int VO> __device__ __forceinline__ void tile_y(LAS unsigned char* lds, float (&l)[2], f32x4 (&o)[2][4], f32x4 (&s)[2][4], int fr, int fq) {
;     bf16x8 pb[NQ][2];
; #pragma unroll
;     for (int q = 0; q < NQ; ++q) {
;         f32x4 (&sq)[4] = s[I0 + q];
;         f32x2_t rs2 = {0.f, 0.f};
; #pragma unroll
;         for (int ss = 0; ss < 4; ++ss) {
; #pragma unroll
;             for (int i = 0; i < 4; ++i) sq[ss][i] = __builtin_amdgcn_exp2f(sq[ss][i]);
;             rs2 += (f32x2_t){sq[ss][0], sq[ss][1]}; rs2 += (f32x2_t){sq[ss][2], sq[ss][3]};
;         }
;         l[I0 + q] += rs2.x + rs2.y;
; #pragma unroll
;         for (int j = 0; j < 2; ++j) {
;             const v4u w = (v4u){cvtpk(sq[2 * j][0], sq[2 * j][1]), cvtpk(sq[2 * j][2], sq[2 * j][3]), cvtpk(sq[2 * j + 1][0], sq[2 * j + 1][1]), cvtpk(sq[2 * j + 1][2], sq[2 * j + 1][3])};
;             pb[q][j] = __builtin_bit_cast(bf16x8, w);
;         }
;     }
; #pragma unroll
;     for (int dt = 0; dt < 4; ++dt)
; #pragma unroll
;         for (int j = 0; j < 2; ++j) {
;             LAS unsigned char* vp = lds + VO + ((32 * j + 4 * fq + (fr >> 2)) * VSTR + 16 * dt + 4 * (fr & 3)) * 2;
;             const s16x4 lo = __builtin_bit_cast(s16x4, __builtin_amdgcn_ds_read_tr16_b64_v4i16((LAS v4i16_t*)vp));
;             const s16x4 hi = __builtin_bit_cast(s16x4, __builtin_amdgcn_ds_read_tr16_b64_v4i16((LAS v4i16_t*)(vp + 16 * VSTR * 2)));
;             const bf16x8 vf = (bf16x8){lo[0], lo[1], lo[2], lo[3], hi[0], hi[1], hi[2], hi[3]};
; #pragma unroll
;             for (int q = 0; q < NQ; ++q) o[I0 + q][dt] = __builtin_amdgcn_mfma_f32_16x16x32_bf16(vf, pb[q][j], o[I0 + q][dt], 0, 0, 0);
;         }
; }
.Lmla_tail0:
	s_cmp_lg_u32 s49, s9
	s_cbranch_scc1 .Lmla_bar0
	ds_read_b64_tr_b16 v[220:221], v251 offset:16384
	ds_read_b64_tr_b16 v[222:223], v251 offset:18944
	ds_read_b64_tr_b16 v[224:225], v251 offset:21504
	ds_read_b64_tr_b16 v[226:227], v251 offset:24064
	ds_read_b64_tr_b16 v[228:229], v251 offset:16416
	ds_read_b64_tr_b16 v[230:231], v251 offset:18976
	ds_read_b64_tr_b16 v[232:233], v251 offset:21536
	ds_read_b64_tr_b16 v[234:235], v251 offset:24096
	ds_read_b64_tr_b16 v[236:237], v251 offset:16448
	ds_read_b64_tr_b16 v[238:239], v251 offset:19008
	ds_read_b64_tr_b16 v[240:241], v251 offset:21568
	ds_read_b64_tr_b16 v[242:243], v251 offset:24128
	ds_read_b64_tr_b16 v[244:245], v251 offset:16480
	ds_read_b64_tr_b16 v[246:247], v251 offset:19040
	v_exp_f32_e32 v100, v100
	v_exp_f32_e32 v101, v101
	v_exp_f32_e32 v102, v102
	v_exp_f32_e32 v103, v103
	v_exp_f32_e32 v104, v104
	v_exp_f32_e32 v105, v105
	v_exp_f32_e32 v106, v106
	v_exp_f32_e32 v107, v107
	v_exp_f32_e32 v108, v108
	v_exp_f32_e32 v109, v109
	v_exp_f32_e32 v110, v110
	v_exp_f32_e32 v111, v111
	v_exp_f32_e32 v112, v112
	v_exp_f32_e32 v113, v113
	v_exp_f32_e32 v114, v114
	v_exp_f32_e32 v115, v115
	v_cvt_pk_bf16_f32 v132, v100, v101
	v_cvt_pk_bf16_f32 v133, v102, v103
	v_cvt_pk_bf16_f32 v134, v104, v105
	v_cvt_pk_bf16_f32 v135, v106, v107
	v_cvt_pk_bf16_f32 v136, v108, v109
	v_cvt_pk_bf16_f32 v137, v110, v111
	v_cvt_pk_bf16_f32 v138, v112, v113
	v_cvt_pk_bf16_f32 v139, v114, v115
	v_add_f32_e32 v100, v100, v101
	v_add_f32_e32 v102, v102, v103
	v_add_f32_e32 v104, v104, v105
	v_add_f32_e32 v106, v106, v107
	v_add_f32_e32 v108, v108, v109
	v_add_f32_e32 v110, v110, v111
	v_add_f32_e32 v112, v112, v113
	v_add_f32_e32 v114, v114, v115
	v_add_f32_e32 v100, v100, v102
	v_add_f32_e32 v104, v104, v106
	v_add_f32_e32 v108, v108, v110
	v_add_f32_e32 v112, v112, v114
	v_add_f32_e32 v100, v100, v104
	v_add_f32_e32 v108, v108, v112
	v_add_f32_e32 v100, v100, v108
	v_add_f32_e32 v165, v165, v100
	v_exp_f32_e32 v116, v116
	v_exp_f32_e32 v117, v117
	v_exp_f32_e32 v118, v118
	v_exp_f32_e32 v119, v119
	v_exp_f32_e32 v120, v120
	v_exp_f32_e32 v121, v121
	v_exp_f32_e32 v122, v122
	v_exp_f32_e32 v123, v123
	v_exp_f32_e32 v124, v124
	v_exp_f32_e32 v125, v125
	v_exp_f32_e32 v126, v126
	v_exp_f32_e32 v127, v127
	v_exp_f32_e32 v128, v128
	v_exp_f32_e32 v129, v129
	v_exp_f32_e32 v130, v130
	v_exp_f32_e32 v131, v131
	v_cvt_pk_bf16_f32 v140, v116, v117
	v_cvt_pk_bf16_f32 v141, v118, v119
	v_cvt_pk_bf16_f32 v142, v120, v121
	v_cvt_pk_bf16_f32 v143, v122, v123
	v_cvt_pk_bf16_f32 v52, v124, v125
	v_cvt_pk_bf16_f32 v53, v126, v127
	v_cvt_pk_bf16_f32 v54, v128, v129
	v_cvt_pk_bf16_f32 v55, v130, v131
	v_add_f32_e32 v116, v116, v117
	v_add_f32_e32 v118, v118, v119
	v_add_f32_e32 v120, v120, v121
	v_add_f32_e32 v122, v122, v123
	v_add_f32_e32 v124, v124, v125
	v_add_f32_e32 v126, v126, v127
	v_add_f32_e32 v128, v128, v129
	v_add_f32_e32 v130, v130, v131
	v_add_f32_e32 v116, v116, v118
	v_add_f32_e32 v120, v120, v122
	v_add_f32_e32 v124, v124, v126
	v_add_f32_e32 v128, v128, v130
	v_add_f32_e32 v116, v116, v120
	v_add_f32_e32 v124, v124, v128
	v_add_f32_e32 v116, v116, v124
	v_add_f32_e32 v164, v164, v116
	s_waitcnt lgkmcnt(0)
	v_mfma_f32_16x16x32_bf16 v[96:99], v[220:223], v[132:135], v[96:99]
	v_mfma_f32_16x16x32_bf16 v[84:87], v[220:223], v[140:143], v[84:87]
	v_mfma_f32_16x16x32_bf16 v[96:99], v[224:227], v[136:139], v[96:99]
	v_mfma_f32_16x16x32_bf16 v[84:87], v[224:227], v[52:55], v[84:87]
	ds_read_b64_tr_b16 v[220:221], v251 offset:21600
	ds_read_b64_tr_b16 v[222:223], v251 offset:24160
	v_mfma_f32_16x16x32_bf16 v[88:91], v[228:231], v[132:135], v[88:91]
	v_mfma_f32_16x16x32_bf16 v[76:79], v[228:231], v[140:143], v[76:79]
	v_mfma_f32_16x16x32_bf16 v[88:91], v[232:235], v[136:139], v[88:91]
	v_mfma_f32_16x16x32_bf16 v[76:79], v[232:235], v[52:55], v[76:79]
	v_mfma_f32_16x16x32_bf16 v[92:95], v[236:239], v[132:135], v[92:95]
	v_mfma_f32_16x16x32_bf16 v[80:83], v[236:239], v[140:143], v[80:83]
	v_mfma_f32_16x16x32_bf16 v[92:95], v[240:243], v[136:139], v[92:95]
	v_mfma_f32_16x16x32_bf16 v[80:83], v[240:243], v[52:55], v[80:83]
	v_mfma_f32_16x16x32_bf16 v[48:51], v[244:247], v[132:135], v[48:51]
	v_mfma_f32_16x16x32_bf16 v[56:59], v[244:247], v[140:143], v[56:59]
	s_waitcnt lgkmcnt(0)
	v_mfma_f32_16x16x32_bf16 v[48:51], v[220:223], v[136:139], v[48:51]
	v_mfma_f32_16x16x32_bf16 v[56:59], v[220:223], v[52:55], v[56:59]
	s_branch .Lmla_bar0

; #define LAS __attribute__((address_space(3)))
; __device__ __forceinline__ unsigned cvtpk(float lo, float hi) { f32x2_t v = {lo, hi}; bf16x2_t b = __builtin_convertvector(v, bf16x2_t); return __builtin_bit_cast(unsigned, b); }
; template <int I0, int NQ, int VO> __device__ __forceinline__ void tile_y(LAS unsigned char* lds, float (&l)[2], f32x4 (&o)[2][4], f32x4 (&s)[2][4], int fr, int fq) {
;     bf16x8 pb[NQ][2];
; #pragma unroll
;     for (int q = 0; q < NQ; ++q) {
;         f32x4 (&sq)[4] = s[I0 + q];
;         f32x2_t rs2 = {0.f, 0.f};
; #pragma unroll
;         for (int ss = 0; ss < 4; ++ss) {
; #pragma unroll
;             for (int i = 0; i < 4; ++i) sq[ss][i] = __builtin_amdgcn_exp2f(sq[ss][i]);
;             rs2 += (f32x2_t){sq[ss][0], sq[ss][1]}; rs2 += (f32x2_t){sq[ss][2], sq[ss][3]};
;         }
;         l[I0 + q] += rs2.x + rs2.y;
; #pragma unroll
;         for (int j = 0; j < 2; ++j) {
;             const v4u w = (v4u){cvtpk(sq[2 * j][0], sq[2 * j][1]), cvtpk(sq[2 * j][2], sq[2 * j][3]), cvtpk(sq[2 * j + 1][0], sq[2 * j + 1][1]), cvtpk(sq[2 * j + 1][2], sq[2 * j + 1][3])};
;             pb[q][j] = __builtin_bit_cast(bf16x8, w);
;         }
;     }
; #pragma unroll
;     for (int dt = 0; dt < 4; ++dt)
; #pragma unroll
;         for (int j = 0; j < 2; ++j) {
;             LAS unsigned char* vp = lds + VO + ((32 * j + 4 * fq + (fr >> 2)) * VSTR + 16 * dt + 4 * (fr & 3)) * 2;
;             const s16x4 lo = __builtin_bit_cast(s16x4, __builtin_amdgcn_ds_read_tr16_b64_v4i16((LAS v4i16_t*)vp));
;             const s16x4 hi = __builtin_bit_cast(s16x4, __builtin_amdgcn_ds_read_tr16_b64_v4i16((LAS v4i16_t*)(vp + 16 * VSTR * 2)));
;             const bf16x8 vf = (bf16x8){lo[0], lo[1], lo[2], lo[3], hi[0], hi[1], hi[2], hi[3]};
; #pragma unroll
;             for (int q = 0; q < NQ; ++q) o[I0 + q][dt] = __builtin_amdgcn_mfma_f32_16x16x32_bf16(vf, pb[q][j], o[I0 + q][dt], 0, 0, 0);
;         }
; }
.Lmla_tail1:
	s_cmp_lg_u32 s49, s9
	s_cbranch_scc1 .Lmla_bar1
	ds_read_b64_tr_b16 v[220:221], v203 offset:16384
	ds_read_b64_tr_b16 v[222:223], v203 offset:18944
	ds_read_b64_tr_b16 v[224:225], v203 offset:21504
	ds_read_b64_tr_b16 v[226:227], v203 offset:24064
	ds_read_b64_tr_b16 v[228:229], v203 offset:16416
	ds_read_b64_tr_b16 v[230:231], v203 offset:18976
	ds_read_b64_tr_b16 v[232:233], v203 offset:21536
	ds_read_b64_tr_b16 v[234:235], v203 offset:24096
	ds_read_b64_tr_b16 v[236:237], v203 offset:16448
	ds_read_b64_tr_b16 v[238:239], v203 offset:19008
	ds_read_b64_tr_b16 v[240:241], v203 offset:21568
	ds_read_b64_tr_b16 v[242:243], v203 offset:24128
	ds_read_b64_tr_b16 v[244:245], v203 offset:16480
	ds_read_b64_tr_b16 v[246:247], v203 offset:19040
	v_exp_f32_e32 v24, v24
	v_exp_f32_e32 v25, v25
	v_exp_f32_e32 v26, v26
	v_exp_f32_e32 v27, v27
	v_exp_f32_e32 v28, v28
	v_exp_f32_e32 v29, v29
	v_exp_f32_e32 v30, v30
	v_exp_f32_e32 v31, v31
	v_exp_f32_e32 v32, v32
	v_exp_f32_e32 v33, v33
	v_exp_f32_e32 v34, v34
	v_exp_f32_e32 v35, v35
	v_exp_f32_e32 v36, v36
	v_exp_f32_e32 v37, v37
	v_exp_f32_e32 v38, v38
	v_exp_f32_e32 v39, v39
	v_cvt_pk_bf16_f32 v132, v24, v25
	v_cvt_pk_bf16_f32 v133, v26, v27
	v_cvt_pk_bf16_f32 v134, v28, v29
	v_cvt_pk_bf16_f32 v135, v30, v31
	v_cvt_pk_bf16_f32 v136, v32, v33
	v_cvt_pk_bf16_f32 v137, v34, v35
	v_cvt_pk_bf16_f32 v138, v36, v37
	v_cvt_pk_bf16_f32 v139, v38, v39
	v_add_f32_e32 v24, v24, v25
	v_add_f32_e32 v26, v26, v27
	v_add_f32_e32 v28, v28, v29
	v_add_f32_e32 v30, v30, v31
	v_add_f32_e32 v32, v32, v33
	v_add_f32_e32 v34, v34, v35
	v_add_f32_e32 v36, v36, v37
	v_add_f32_e32 v38, v38, v39
	v_add_f32_e32 v24, v24, v26
	v_add_f32_e32 v28, v28, v30
	v_add_f32_e32 v32, v32, v34
	v_add_f32_e32 v36, v36, v38
	v_add_f32_e32 v24, v24, v28
	v_add_f32_e32 v32, v32, v36
	v_add_f32_e32 v24, v24, v32
	v_add_f32_e32 v165, v165, v24
	v_exp_f32_e32 v40, v40
	v_exp_f32_e32 v41, v41
	v_exp_f32_e32 v42, v42
	v_exp_f32_e32 v43, v43
	v_exp_f32_e32 v44, v44
	v_exp_f32_e32 v45, v45
	v_exp_f32_e32 v46, v46
	v_exp_f32_e32 v47, v47
	v_exp_f32_e32 v212, v212
	v_exp_f32_e32 v213, v213
	v_exp_f32_e32 v214, v214
	v_exp_f32_e32 v215, v215
	v_exp_f32_e32 v216, v216
	v_exp_f32_e32 v217, v217
	v_exp_f32_e32 v218, v218
	v_exp_f32_e32 v219, v219
	v_cvt_pk_bf16_f32 v140, v40, v41
	v_cvt_pk_bf16_f32 v141, v42, v43
	v_cvt_pk_bf16_f32 v142, v44, v45
	v_cvt_pk_bf16_f32 v143, v46, v47
	v_cvt_pk_bf16_f32 v52, v212, v213
	v_cvt_pk_bf16_f32 v53, v214, v215
	v_cvt_pk_bf16_f32 v54, v216, v217
	v_cvt_pk_bf16_f32 v55, v218, v219
	v_add_f32_e32 v40, v40, v41
	v_add_f32_e32 v42, v42, v43
	v_add_f32_e32 v44, v44, v45
	v_add_f32_e32 v46, v46, v47
	v_add_f32_e32 v212, v212, v213
	v_add_f32_e32 v214, v214, v215
	v_add_f32_e32 v216, v216, v217
	v_add_f32_e32 v218, v218, v219
	v_add_f32_e32 v40, v40, v42
	v_add_f32_e32 v44, v44, v46
	v_add_f32_e32 v212, v212, v214
	v_add_f32_e32 v216, v216, v218
	v_add_f32_e32 v40, v40, v44
	v_add_f32_e32 v212, v212, v216
	v_add_f32_e32 v40, v40, v212
	v_add_f32_e32 v164, v164, v40
	s_waitcnt lgkmcnt(0)
	v_mfma_f32_16x16x32_bf16 v[96:99], v[220:223], v[132:135], v[96:99]
	v_mfma_f32_16x16x32_bf16 v[84:87], v[220:223], v[140:143], v[84:87]
	v_mfma_f32_16x16x32_bf16 v[96:99], v[224:227], v[136:139], v[96:99]
	v_mfma_f32_16x16x32_bf16 v[84:87], v[224:227], v[52:55], v[84:87]
	ds_read_b64_tr_b16 v[220:221], v203 offset:21600
	ds_read_b64_tr_b16 v[222:223], v203 offset:24160
	v_mfma_f32_16x16x32_bf16 v[88:91], v[228:231], v[132:135], v[88:91]
	v_mfma_f32_16x16x32_bf16 v[76:79], v[228:231], v[140:143], v[76:79]
	v_mfma_f32_16x16x32_bf16 v[88:91], v[232:235], v[136:139], v[88:91]
	v_mfma_f32_16x16x32_bf16 v[76:79], v[232:235], v[52:55], v[76:79]
	v_mfma_f32_16x16x32_bf16 v[92:95], v[236:239], v[132:135], v[92:95]
	v_mfma_f32_16x16x32_bf16 v[80:83], v[236:239], v[140:143], v[80:83]
	v_mfma_f32_16x16x32_bf16 v[92:95], v[240:243], v[136:139], v[92:95]
	v_mfma_f32_16x16x32_bf16 v[80:83], v[240:243], v[52:55], v[80:83]
	v_mfma_f32_16x16x32_bf16 v[48:51], v[244:247], v[132:135], v[48:51]
	v_mfma_f32_16x16x32_bf16 v[56:59], v[244:247], v[140:143], v[56:59]
	s_waitcnt lgkmcnt(0)
	v_mfma_f32_16x16x32_bf16 v[48:51], v[220:223], v[136:139], v[48:51]
	v_mfma_f32_16x16x32_bf16 v[56:59], v[220:223], v[52:55], v[56:59]
	s_branch .Lmla_bar1

; #define LAS __attribute__((address_space(3)))
; __device__ __forceinline__ unsigned cvtpk(float lo, float hi) { f32x2_t v = {lo, hi}; bf16x2_t b = __builtin_convertvector(v, bf16x2_t); return __builtin_bit_cast(unsigned, b); }
; template <int I0, int NQ, int VO> __device__ __forceinline__ void tile_y(LAS unsigned char* lds, float (&l)[2], f32x4 (&o)[2][4], f32x4 (&s)[2][4], int fr, int fq) {
;     bf16x8 pb[NQ][2];
; #pragma unroll
;     for (int q = 0; q < NQ; ++q) {
;         f32x4 (&sq)[4] = s[I0 + q];
;         f32x2_t rs2 = {0.f, 0.f};
; #pragma unroll
;         for (int ss = 0; ss < 4; ++ss) {
; #pragma unroll
;             for (int i = 0; i < 4; ++i) sq[ss][i] = __builtin_amdgcn_exp2f(sq[ss][i]);
;             rs2 += (f32x2_t){sq[ss][0], sq[ss][1]}; rs2 += (f32x2_t){sq[ss][2], sq[ss][3]};
;         }
;         l[I0 + q] += rs2.x + rs2.y;
; #pragma unroll
;         for (int j = 0; j < 2; ++j) {
;             const v4u w = (v4u){cvtpk(sq[2 * j][0], sq[2 * j][1]), cvtpk(sq[2 * j][2], sq[2 * j][3]), cvtpk(sq[2 * j + 1][0], sq[2 * j + 1][1]), cvtpk(sq[2 * j + 1][2], sq[2 * j + 1][3])};
;             pb[q][j] = __builtin_bit_cast(bf16x8, w);
;         }
;     }
; #pragma unroll
;     for (int dt = 0; dt < 4; ++dt)
; #pragma unroll
;         for (int j = 0; j < 2; ++j) {
;             LAS unsigned char* vp = lds + VO + ((32 * j + 4 * fq + (fr >> 2)) * VSTR + 16 * dt + 4 * (fr & 3)) * 2;
;             const s16x4 lo = __builtin_bit_cast(s16x4, __builtin_amdgcn_ds_read_tr16_b64_v4i16((LAS v4i16_t*)vp));
;             const s16x4 hi = __builtin_bit_cast(s16x4, __builtin_amdgcn_ds_read_tr16_b64_v4i16((LAS v4i16_t*)(vp + 16 * VSTR * 2)));
;             const bf16x8 vf = (bf16x8){lo[0], lo[1], lo[2], lo[3], hi[0], hi[1], hi[2], hi[3]};
; #pragma unroll
;             for (int q = 0; q < NQ; ++q) o[I0 + q][dt] = __builtin_amdgcn_mfma_f32_16x16x32_bf16(vf, pb[q][j], o[I0 + q][dt], 0, 0, 0);
;         }
; }
.Lmla_tail2:
	s_cmp_lg_u32 s49, s9
	s_cbranch_scc1 .Lmla_bar2
	ds_read_b64_tr_b16 v[220:221], v203 offset:43008
	ds_read_b64_tr_b16 v[222:223], v203 offset:45568
	ds_read_b64_tr_b16 v[224:225], v203 offset:48128
	ds_read_b64_tr_b16 v[226:227], v203 offset:50688
	ds_read_b64_tr_b16 v[228:229], v203 offset:43040
	ds_read_b64_tr_b16 v[230:231], v203 offset:45600
	ds_read_b64_tr_b16 v[232:233], v203 offset:48160
	ds_read_b64_tr_b16 v[234:235], v203 offset:50720
	ds_read_b64_tr_b16 v[236:237], v203 offset:43072
	ds_read_b64_tr_b16 v[238:239], v203 offset:45632
	ds_read_b64_tr_b16 v[240:241], v203 offset:48192
	ds_read_b64_tr_b16 v[242:243], v203 offset:50752
	ds_read_b64_tr_b16 v[244:245], v203 offset:43104
	ds_read_b64_tr_b16 v[246:247], v203 offset:45664
	v_exp_f32_e32 v100, v100
	v_exp_f32_e32 v101, v101
	v_exp_f32_e32 v102, v102
	v_exp_f32_e32 v103, v103
	v_exp_f32_e32 v104, v104
	v_exp_f32_e32 v105, v105
	v_exp_f32_e32 v106, v106
	v_exp_f32_e32 v107, v107
	v_exp_f32_e32 v108, v108
	v_exp_f32_e32 v109, v109
	v_exp_f32_e32 v110, v110
	v_exp_f32_e32 v111, v111
	v_exp_f32_e32 v112, v112
	v_exp_f32_e32 v113, v113
	v_exp_f32_e32 v114, v114
	v_exp_f32_e32 v115, v115
	v_cvt_pk_bf16_f32 v132, v100, v101
	v_cvt_pk_bf16_f32 v133, v102, v103
	v_cvt_pk_bf16_f32 v134, v104, v105
	v_cvt_pk_bf16_f32 v135, v106, v107
	v_cvt_pk_bf16_f32 v136, v108, v109
	v_cvt_pk_bf16_f32 v137, v110, v111
	v_cvt_pk_bf16_f32 v138, v112, v113
	v_cvt_pk_bf16_f32 v139, v114, v115
	v_add_f32_e32 v100, v100, v101
	v_add_f32_e32 v102, v102, v103
	v_add_f32_e32 v104, v104, v105
	v_add_f32_e32 v106, v106, v107
	v_add_f32_e32 v108, v108, v109
	v_add_f32_e32 v110, v110, v111
	v_add_f32_e32 v112, v112, v113
	v_add_f32_e32 v114, v114, v115
	v_add_f32_e32 v100, v100, v102
	v_add_f32_e32 v104, v104, v106
	v_add_f32_e32 v108, v108, v110
	v_add_f32_e32 v112, v112, v114
	v_add_f32_e32 v100, v100, v104
	v_add_f32_e32 v108, v108, v112
	v_add_f32_e32 v100, v100, v108
	v_add_f32_e32 v165, v165, v100
	v_exp_f32_e32 v116, v116
	v_exp_f32_e32 v117, v117
	v_exp_f32_e32 v118, v118
	v_exp_f32_e32 v119, v119
	v_exp_f32_e32 v120, v120
	v_exp_f32_e32 v121, v121
	v_exp_f32_e32 v122, v122
	v_exp_f32_e32 v123, v123
	v_exp_f32_e32 v124, v124
	v_exp_f32_e32 v125, v125
	v_exp_f32_e32 v126, v126
	v_exp_f32_e32 v127, v127
	v_exp_f32_e32 v128, v128
	v_exp_f32_e32 v129, v129
	v_exp_f32_e32 v130, v130
	v_exp_f32_e32 v131, v131
	v_cvt_pk_bf16_f32 v140, v116, v117
	v_cvt_pk_bf16_f32 v141, v118, v119
	v_cvt_pk_bf16_f32 v142, v120, v121
	v_cvt_pk_bf16_f32 v143, v122, v123
	v_cvt_pk_bf16_f32 v52, v124, v125
	v_cvt_pk_bf16_f32 v53, v126, v127
	v_cvt_pk_bf16_f32 v54, v128, v129
	v_cvt_pk_bf16_f32 v55, v130, v131
	v_add_f32_e32 v116, v116, v117
	v_add_f32_e32 v118, v118, v119
	v_add_f32_e32 v120, v120, v121
	v_add_f32_e32 v122, v122, v123
	v_add_f32_e32 v124, v124, v125
	v_add_f32_e32 v126, v126, v127
	v_add_f32_e32 v128, v128, v129
	v_add_f32_e32 v130, v130, v131
	v_add_f32_e32 v116, v116, v118
	v_add_f32_e32 v120, v120, v122
	v_add_f32_e32 v124, v124, v126
	v_add_f32_e32 v128, v128, v130
	v_add_f32_e32 v116, v116, v120
	v_add_f32_e32 v124, v124, v128
	v_add_f32_e32 v116, v116, v124
	v_add_f32_e32 v164, v164, v116
	s_waitcnt lgkmcnt(0)
	v_mfma_f32_16x16x32_bf16 v[96:99], v[220:223], v[132:135], v[96:99]
	v_mfma_f32_16x16x32_bf16 v[84:87], v[220:223], v[140:143], v[84:87]
	v_mfma_f32_16x16x32_bf16 v[96:99], v[224:227], v[136:139], v[96:99]
	v_mfma_f32_16x16x32_bf16 v[84:87], v[224:227], v[52:55], v[84:87]
	ds_read_b64_tr_b16 v[220:221], v203 offset:48224
	ds_read_b64_tr_b16 v[222:223], v203 offset:50784
	v_mfma_f32_16x16x32_bf16 v[88:91], v[228:231], v[132:135], v[88:91]
	v_mfma_f32_16x16x32_bf16 v[76:79], v[228:231], v[140:143], v[76:79]
	v_mfma_f32_16x16x32_bf16 v[88:91], v[232:235], v[136:139], v[88:91]
	v_mfma_f32_16x16x32_bf16 v[76:79], v[232:235], v[52:55], v[76:79]
	v_mfma_f32_16x16x32_bf16 v[92:95], v[236:239], v[132:135], v[92:95]
	v_mfma_f32_16x16x32_bf16 v[80:83], v[236:239], v[140:143], v[80:83]
	v_mfma_f32_16x16x32_bf16 v[92:95], v[240:243], v[136:139], v[92:95]
	v_mfma_f32_16x16x32_bf16 v[80:83], v[240:243], v[52:55], v[80:83]
	v_mfma_f32_16x16x32_bf16 v[48:51], v[244:247], v[132:135], v[48:51]
	v_mfma_f32_16x16x32_bf16 v[56:59], v[244:247], v[140:143], v[56:59]
	s_waitcnt lgkmcnt(0)
	v_mfma_f32_16x16x32_bf16 v[48:51], v[220:223], v[136:139], v[48:51]
	v_mfma_f32_16x16x32_bf16 v[56:59], v[220:223], v[52:55], v[56:59]
	s_branch .Lmla_bar2

; #define LAS __attribute__((address_space(3)))
; __device__ __forceinline__ unsigned cvtpk(float lo, float hi) { f32x2_t v = {lo, hi}; bf16x2_t b = __builtin_convertvector(v, bf16x2_t); return __builtin_bit_cast(unsigned, b); }
; template <int I0, int NQ, int VO> __device__ __forceinline__ void tile_y(LAS unsigned char* lds, float (&l)[2], f32x4 (&o)[2][4], f32x4 (&s)[2][4], int fr, int fq) {
;     bf16x8 pb[NQ][2];
; #pragma unroll
;     for (int q = 0; q < NQ; ++q) {
;         f32x4 (&sq)[4] = s[I0 + q];
;         f32x2_t rs2 = {0.f, 0.f};
; #pragma unroll
;         for (int ss = 0; ss < 4; ++ss) {
; #pragma unroll
;             for (int i = 0; i < 4; ++i) sq[ss][i] = __builtin_amdgcn_exp2f(sq[ss][i]);
;             rs2 += (f32x2_t){sq[ss][0], sq[ss][1]}; rs2 += (f32x2_t){sq[ss][2], sq[ss][3]};
;         }
;         l[I0 + q] += rs2.x + rs2.y;
; #pragma unroll
;         for (int j = 0; j < 2; ++j) {
;             const v4u w = (v4u){cvtpk(sq[2 * j][0], sq[2 * j][1]), cvtpk(sq[2 * j][2], sq[2 * j][3]), cvtpk(sq[2 * j + 1][0], sq[2 * j + 1][1]), cvtpk(sq[2 * j + 1][2], sq[2 * j + 1][3])};
;             pb[q][j] = __builtin_bit_cast(bf16x8, w);
;         }
;     }
; #pragma unroll
;     for (int dt = 0; dt < 4; ++dt)
; #pragma unroll
;         for (int j = 0; j < 2; ++j) {
;             LAS unsigned char* vp = lds + VO + ((32 * j + 4 * fq + (fr >> 2)) * VSTR + 16 * dt + 4 * (fr & 3)) * 2;
;             const s16x4 lo = __builtin_bit_cast(s16x4, __builtin_amdgcn_ds_read_tr16_b64_v4i16((LAS v4i16_t*)vp));
;             const s16x4 hi = __builtin_bit_cast(s16x4, __builtin_amdgcn_ds_read_tr16_b64_v4i16((LAS v4i16_t*)(vp + 16 * VSTR * 2)));
;             const bf16x8 vf = (bf16x8){lo[0], lo[1], lo[2], lo[3], hi[0], hi[1], hi[2], hi[3]};
; #pragma unroll
;             for (int q = 0; q < NQ; ++q) o[I0 + q][dt] = __builtin_amdgcn_mfma_f32_16x16x32_bf16(vf, pb[q][j], o[I0 + q][dt], 0, 0, 0);
;         }
; }
.Lmla_tail3:
	s_cmp_lg_u32 s49, s9
	s_cbranch_scc1 .Lmla_bar3
	ds_read_b64_tr_b16 v[220:221], v251 offset:16384
	ds_read_b64_tr_b16 v[222:223], v251 offset:18944
	ds_read_b64_tr_b16 v[224:225], v251 offset:21504
	ds_read_b64_tr_b16 v[226:227], v251 offset:24064
	ds_read_b64_tr_b16 v[228:229], v251 offset:16416
	ds_read_b64_tr_b16 v[230:231], v251 offset:18976
	ds_read_b64_tr_b16 v[232:233], v251 offset:21536
	ds_read_b64_tr_b16 v[234:235], v251 offset:24096
	ds_read_b64_tr_b16 v[236:237], v251 offset:16448
	ds_read_b64_tr_b16 v[238:239], v251 offset:19008
	ds_read_b64_tr_b16 v[240:241], v251 offset:21568
	ds_read_b64_tr_b16 v[242:243], v251 offset:24128
	ds_read_b64_tr_b16 v[244:245], v251 offset:16480
	ds_read_b64_tr_b16 v[246:247], v251 offset:19040
	v_exp_f32_e32 v24, v24
	v_exp_f32_e32 v25, v25
	v_exp_f32_e32 v26, v26
	v_exp_f32_e32 v27, v27
	v_exp_f32_e32 v28, v28
	v_exp_f32_e32 v29, v29
	v_exp_f32_e32 v30, v30
	v_exp_f32_e32 v31, v31
	v_exp_f32_e32 v32, v32
	v_exp_f32_e32 v33, v33
	v_exp_f32_e32 v34, v34
	v_exp_f32_e32 v35, v35
	v_exp_f32_e32 v36, v36
	v_exp_f32_e32 v37, v37
	v_exp_f32_e32 v38, v38
	v_exp_f32_e32 v39, v39
	v_cvt_pk_bf16_f32 v132, v24, v25
	v_cvt_pk_bf16_f32 v133, v26, v27
	v_cvt_pk_bf16_f32 v134, v28, v29
	v_cvt_pk_bf16_f32 v135, v30, v31
	v_cvt_pk_bf16_f32 v136, v32, v33
	v_cvt_pk_bf16_f32 v137, v34, v35
	v_cvt_pk_bf16_f32 v138, v36, v37
	v_cvt_pk_bf16_f32 v139, v38, v39
	v_add_f32_e32 v24, v24, v25
	v_add_f32_e32 v26, v26, v27
	v_add_f32_e32 v28, v28, v29
	v_add_f32_e32 v30, v30, v31
	v_add_f32_e32 v32, v32, v33
	v_add_f32_e32 v34, v34, v35
	v_add_f32_e32 v36, v36, v37
	v_add_f32_e32 v38, v38, v39
	v_add_f32_e32 v24, v24, v26
	v_add_f32_e32 v28, v28, v30
	v_add_f32_e32 v32, v32, v34
	v_add_f32_e32 v36, v36, v38
	v_add_f32_e32 v24, v24, v28
	v_add_f32_e32 v32, v32, v36
	v_add_f32_e32 v24, v24, v32
	v_add_f32_e32 v165, v165, v24
	v_exp_f32_e32 v40, v40
	v_exp_f32_e32 v41, v41
	v_exp_f32_e32 v42, v42
	v_exp_f32_e32 v43, v43
	v_exp_f32_e32 v44, v44
	v_exp_f32_e32 v45, v45
	v_exp_f32_e32 v46, v46
	v_exp_f32_e32 v47, v47
	v_exp_f32_e32 v212, v212
	v_exp_f32_e32 v213, v213
	v_exp_f32_e32 v214, v214
	v_exp_f32_e32 v215, v215
	v_exp_f32_e32 v216, v216
	v_exp_f32_e32 v217, v217
	v_exp_f32_e32 v218, v218
	v_exp_f32_e32 v219, v219
	v_cvt_pk_bf16_f32 v140, v40, v41
	v_cvt_pk_bf16_f32 v141, v42, v43
	v_cvt_pk_bf16_f32 v142, v44, v45
	v_cvt_pk_bf16_f32 v143, v46, v47
	v_cvt_pk_bf16_f32 v52, v212, v213
	v_cvt_pk_bf16_f32 v53, v214, v215
	v_cvt_pk_bf16_f32 v54, v216, v217
	v_cvt_pk_bf16_f32 v55, v218, v219
	v_add_f32_e32 v40, v40, v41
	v_add_f32_e32 v42, v42, v43
	v_add_f32_e32 v44, v44, v45
	v_add_f32_e32 v46, v46, v47
	v_add_f32_e32 v212, v212, v213
	v_add_f32_e32 v214, v214, v215
	v_add_f32_e32 v216, v216, v217
	v_add_f32_e32 v218, v218, v219
	v_add_f32_e32 v40, v40, v42
	v_add_f32_e32 v44, v44, v46
	v_add_f32_e32 v212, v212, v214
	v_add_f32_e32 v216, v216, v218
	v_add_f32_e32 v40, v40, v44
	v_add_f32_e32 v212, v212, v216
	v_add_f32_e32 v40, v40, v212
	v_add_f32_e32 v164, v164, v40
	s_waitcnt lgkmcnt(0)
	v_mfma_f32_16x16x32_bf16 v[96:99], v[220:223], v[132:135], v[96:99]
	v_mfma_f32_16x16x32_bf16 v[84:87], v[220:223], v[140:143], v[84:87]
	v_mfma_f32_16x16x32_bf16 v[96:99], v[224:227], v[136:139], v[96:99]
	v_mfma_f32_16x16x32_bf16 v[84:87], v[224:227], v[52:55], v[84:87]
	ds_read_b64_tr_b16 v[220:221], v251 offset:21600
	ds_read_b64_tr_b16 v[222:223], v251 offset:24160
	v_mfma_f32_16x16x32_bf16 v[88:91], v[228:231], v[132:135], v[88:91]
	v_mfma_f32_16x16x32_bf16 v[76:79], v[228:231], v[140:143], v[76:79]
	v_mfma_f32_16x16x32_bf16 v[88:91], v[232:235], v[136:139], v[88:91]
	v_mfma_f32_16x16x32_bf16 v[76:79], v[232:235], v[52:55], v[76:79]
	v_mfma_f32_16x16x32_bf16 v[92:95], v[236:239], v[132:135], v[92:95]
	v_mfma_f32_16x16x32_bf16 v[80:83], v[236:239], v[140:143], v[80:83]
	v_mfma_f32_16x16x32_bf16 v[92:95], v[240:243], v[136:139], v[92:95]
	v_mfma_f32_16x16x32_bf16 v[80:83], v[240:243], v[52:55], v[80:83]
	v_mfma_f32_16x16x32_bf16 v[48:51], v[244:247], v[132:135], v[48:51]
	v_mfma_f32_16x16x32_bf16 v[56:59], v[244:247], v[140:143], v[56:59]
	s_waitcnt lgkmcnt(0)
	v_mfma_f32_16x16x32_bf16 v[48:51], v[220:223], v[136:139], v[48:51]
	v_mfma_f32_16x16x32_bf16 v[56:59], v[220:223], v[52:55], v[56:59]
	s_branch .Lmla_bar3

; #define LAS __attribute__((address_space(3)))
; __device__ __forceinline__ unsigned cvtpk(float lo, float hi) { f32x2_t v = {lo, hi}; bf16x2_t b = __builtin_convertvector(v, bf16x2_t); return __builtin_bit_cast(unsigned, b); }
; template <int I0, int NQ, int VO> __device__ __forceinline__ void tile_y(LAS unsigned char* lds, float (&l)[2], f32x4 (&o)[2][4], f32x4 (&s)[2][4], int fr, int fq) {
;     bf16x8 pb[NQ][2];
; #pragma unroll
;     for (int q = 0; q < NQ; ++q) {
;         f32x4 (&sq)[4] = s[I0 + q];
;         f32x2_t rs2 = {0.f, 0.f};
; #pragma unroll
;         for (int ss = 0; ss < 4; ++ss) {
; #pragma unroll
;             for (int i = 0; i < 4; ++i) sq[ss][i] = __builtin_amdgcn_exp2f(sq[ss][i]);
;             rs2 += (f32x2_t){sq[ss][0], sq[ss][1]}; rs2 += (f32x2_t){sq[ss][2], sq[ss][3]};
;         }
;         l[I0 + q] += rs2.x + rs2.y;
; #pragma unroll
;         for (int j = 0; j < 2; ++j) {
;             const v4u w = (v4u){cvtpk(sq[2 * j][0], sq[2 * j][1]), cvtpk(sq[2 * j][2], sq[2 * j][3]), cvtpk(sq[2 * j + 1][0], sq[2 * j + 1][1]), cvtpk(sq[2 * j + 1][2], sq[2 * j + 1][3])};
;             pb[q][j] = __builtin_bit_cast(bf16x8, w);
;         }
;     }
; #pragma unroll
;     for (int dt = 0; dt < 4; ++dt)
; #pragma unroll
;         for (int j = 0; j < 2; ++j) {
;             LAS unsigned char* vp = lds + VO + ((32 * j + 4 * fq + (fr >> 2)) * VSTR + 16 * dt + 4 * (fr & 3)) * 2;
;             const s16x4 lo = __builtin_bit_cast(s16x4, __builtin_amdgcn_ds_read_tr16_b64_v4i16((LAS v4i16_t*)vp));
;             const s16x4 hi = __builtin_bit_cast(s16x4, __builtin_amdgcn_ds_read_tr16_b64_v4i16((LAS v4i16_t*)(vp + 16 * VSTR * 2)));
;             const bf16x8 vf = (bf16x8){lo[0], lo[1], lo[2], lo[3], hi[0], hi[1], hi[2], hi[3]};
; #pragma unroll
;             for (int q = 0; q < NQ; ++q) o[I0 + q][dt] = __builtin_amdgcn_mfma_f32_16x16x32_bf16(vf, pb[q][j], o[I0 + q][dt], 0, 0, 0);
;         }
; }
.Lmla_tail4:
	s_cmp_lg_u32 s49, s9
	s_cbranch_scc1 .Lmla_bar4
	ds_read_b64_tr_b16 v[220:221], v203 offset:16384
	ds_read_b64_tr_b16 v[222:223], v203 offset:18944
	ds_read_b64_tr_b16 v[224:225], v203 offset:21504
	ds_read_b64_tr_b16 v[226:227], v203 offset:24064
	ds_read_b64_tr_b16 v[228:229], v203 offset:16416
	ds_read_b64_tr_b16 v[230:231], v203 offset:18976
	ds_read_b64_tr_b16 v[232:233], v203 offset:21536
	ds_read_b64_tr_b16 v[234:235], v203 offset:24096
	ds_read_b64_tr_b16 v[236:237], v203 offset:16448
	ds_read_b64_tr_b16 v[238:239], v203 offset:19008
	ds_read_b64_tr_b16 v[240:241], v203 offset:21568
	ds_read_b64_tr_b16 v[242:243], v203 offset:24128
	ds_read_b64_tr_b16 v[244:245], v203 offset:16480
	ds_read_b64_tr_b16 v[246:247], v203 offset:19040
	v_exp_f32_e32 v100, v100
	v_exp_f32_e32 v101, v101
	v_exp_f32_e32 v102, v102
	v_exp_f32_e32 v103, v103
	v_exp_f32_e32 v104, v104
	v_exp_f32_e32 v105, v105
	v_exp_f32_e32 v106, v106
	v_exp_f32_e32 v107, v107
	v_exp_f32_e32 v108, v108
	v_exp_f32_e32 v109, v109
	v_exp_f32_e32 v110, v110
	v_exp_f32_e32 v111, v111
	v_exp_f32_e32 v112, v112
	v_exp_f32_e32 v113, v113
	v_exp_f32_e32 v114, v114
	v_exp_f32_e32 v115, v115
	v_cvt_pk_bf16_f32 v132, v100, v101
	v_cvt_pk_bf16_f32 v133, v102, v103
	v_cvt_pk_bf16_f32 v134, v104, v105
	v_cvt_pk_bf16_f32 v135, v106, v107
	v_cvt_pk_bf16_f32 v136, v108, v109
	v_cvt_pk_bf16_f32 v137, v110, v111
	v_cvt_pk_bf16_f32 v138, v112, v113
	v_cvt_pk_bf16_f32 v139, v114, v115
	v_add_f32_e32 v100, v100, v101
	v_add_f32_e32 v102, v102, v103
	v_add_f32_e32 v104, v104, v105
	v_add_f32_e32 v106, v106, v107
	v_add_f32_e32 v108, v108, v109
	v_add_f32_e32 v110, v110, v111
	v_add_f32_e32 v112, v112, v113
	v_add_f32_e32 v114, v114, v115
	v_add_f32_e32 v100, v100, v102
	v_add_f32_e32 v104, v104, v106
	v_add_f32_e32 v108, v108, v110
	v_add_f32_e32 v112, v112, v114
	v_add_f32_e32 v100, v100, v104
	v_add_f32_e32 v108, v108, v112
	v_add_f32_e32 v100, v100, v108
	v_add_f32_e32 v165, v165, v100
	v_exp_f32_e32 v116, v116
	v_exp_f32_e32 v117, v117
	v_exp_f32_e32 v118, v118
	v_exp_f32_e32 v119, v119
	v_exp_f32_e32 v120, v120
	v_exp_f32_e32 v121, v121
	v_exp_f32_e32 v122, v122
	v_exp_f32_e32 v123, v123
	v_exp_f32_e32 v124, v124
	v_exp_f32_e32 v125, v125
	v_exp_f32_e32 v126, v126
	v_exp_f32_e32 v127, v127
	v_exp_f32_e32 v128, v128
	v_exp_f32_e32 v129, v129
	v_exp_f32_e32 v130, v130
	v_exp_f32_e32 v131, v131
	v_cvt_pk_bf16_f32 v140, v116, v117
	v_cvt_pk_bf16_f32 v141, v118, v119
	v_cvt_pk_bf16_f32 v142, v120, v121
	v_cvt_pk_bf16_f32 v143, v122, v123
	v_cvt_pk_bf16_f32 v52, v124, v125
	v_cvt_pk_bf16_f32 v53, v126, v127
	v_cvt_pk_bf16_f32 v54, v128, v129
	v_cvt_pk_bf16_f32 v55, v130, v131
	v_add_f32_e32 v116, v116, v117
	v_add_f32_e32 v118, v118, v119
	v_add_f32_e32 v120, v120, v121
	v_add_f32_e32 v122, v122, v123
	v_add_f32_e32 v124, v124, v125
	v_add_f32_e32 v126, v126, v127
	v_add_f32_e32 v128, v128, v129
	v_add_f32_e32 v130, v130, v131
	v_add_f32_e32 v116, v116, v118
	v_add_f32_e32 v120, v120, v122
	v_add_f32_e32 v124, v124, v126
	v_add_f32_e32 v128, v128, v130
	v_add_f32_e32 v116, v116, v120
	v_add_f32_e32 v124, v124, v128
	v_add_f32_e32 v116, v116, v124
	v_add_f32_e32 v164, v164, v116
	s_waitcnt lgkmcnt(0)
	v_mfma_f32_16x16x32_bf16 v[96:99], v[220:223], v[132:135], v[96:99]
	v_mfma_f32_16x16x32_bf16 v[84:87], v[220:223], v[140:143], v[84:87]
	v_mfma_f32_16x16x32_bf16 v[96:99], v[224:227], v[136:139], v[96:99]
	v_mfma_f32_16x16x32_bf16 v[84:87], v[224:227], v[52:55], v[84:87]
	ds_read_b64_tr_b16 v[220:221], v203 offset:21600
	ds_read_b64_tr_b16 v[222:223], v203 offset:24160
	v_mfma_f32_16x16x32_bf16 v[88:91], v[228:231], v[132:135], v[88:91]
	v_mfma_f32_16x16x32_bf16 v[76:79], v[228:231], v[140:143], v[76:79]
	v_mfma_f32_16x16x32_bf16 v[88:91], v[232:235], v[136:139], v[88:91]
	v_mfma_f32_16x16x32_bf16 v[76:79], v[232:235], v[52:55], v[76:79]
	v_mfma_f32_16x16x32_bf16 v[92:95], v[236:239], v[132:135], v[92:95]
	v_mfma_f32_16x16x32_bf16 v[80:83], v[236:239], v[140:143], v[80:83]
	v_mfma_f32_16x16x32_bf16 v[92:95], v[240:243], v[136:139], v[92:95]
	v_mfma_f32_16x16x32_bf16 v[80:83], v[240:243], v[52:55], v[80:83]
	v_mfma_f32_16x16x32_bf16 v[48:51], v[244:247], v[132:135], v[48:51]
	v_mfma_f32_16x16x32_bf16 v[56:59], v[244:247], v[140:143], v[56:59]
	s_waitcnt lgkmcnt(0)
	v_mfma_f32_16x16x32_bf16 v[48:51], v[220:223], v[136:139], v[48:51]
	v_mfma_f32_16x16x32_bf16 v[56:59], v[220:223], v[52:55], v[56:59]
	s_branch .Lmla_bar4

; #define LAS __attribute__((address_space(3)))
; __device__ __forceinline__ unsigned cvtpk(float lo, float hi) { f32x2_t v = {lo, hi}; bf16x2_t b = __builtin_convertvector(v, bf16x2_t); return __builtin_bit_cast(unsigned, b); }
; template <int I0, int NQ, int VO> __device__ __forceinline__ void tile_y(LAS unsigned char* lds, float (&l)[2], f32x4 (&o)[2][4], f32x4 (&s)[2][4], int fr, int fq) {
;     bf16x8 pb[NQ][2];
; #pragma unroll
;     for (int q = 0; q < NQ; ++q) {
;         f32x4 (&sq)[4] = s[I0 + q];
;         f32x2_t rs2 = {0.f, 0.f};
; #pragma unroll
;         for (int ss = 0; ss < 4; ++ss) {
; #pragma unroll
;             for (int i = 0; i < 4; ++i) sq[ss][i] = __builtin_amdgcn_exp2f(sq[ss][i]);
;             rs2 += (f32x2_t){sq[ss][0], sq[ss][1]}; rs2 += (f32x2_t){sq[ss][2], sq[ss][3]};
;         }
;         l[I0 + q] += rs2.x + rs2.y;
; #pragma unroll
;         for (int j = 0; j < 2; ++j) {
;             const v4u w = (v4u){cvtpk(sq[2 * j][0], sq[2 * j][1]), cvtpk(sq[2 * j][2], sq[2 * j][3]), cvtpk(sq[2 * j + 1][0], sq[2 * j + 1][1]), cvtpk(sq[2 * j + 1][2], sq[2 * j + 1][3])};
;             pb[q][j] = __builtin_bit_cast(bf16x8, w);
;         }
;     }
; #pragma unroll
;     for (int dt = 0; dt < 4; ++dt)
; #pragma unroll
;         for (int j = 0; j < 2; ++j) {
;             LAS unsigned char* vp = lds + VO + ((32 * j + 4 * fq + (fr >> 2)) * VSTR + 16 * dt + 4 * (fr & 3)) * 2;
;             const s16x4 lo = __builtin_bit_cast(s16x4, __builtin_amdgcn_ds_read_tr16_b64_v4i16((LAS v4i16_t*)vp));
;             const s16x4 hi = __builtin_bit_cast(s16x4, __builtin_amdgcn_ds_read_tr16_b64_v4i16((LAS v4i16_t*)(vp + 16 * VSTR * 2)));
;             const bf16x8 vf = (bf16x8){lo[0], lo[1], lo[2], lo[3], hi[0], hi[1], hi[2], hi[3]};
; #pragma unroll
;             for (int q = 0; q < NQ; ++q) o[I0 + q][dt] = __builtin_amdgcn_mfma_f32_16x16x32_bf16(vf, pb[q][j], o[I0 + q][dt], 0, 0, 0);
;         }
; }
.Lmla_tail5:
	s_cmp_lg_u32 s49, s9
	s_cbranch_scc1 .Lmla_bar5
	ds_read_b64_tr_b16 v[220:221], v203 offset:43008
	ds_read_b64_tr_b16 v[222:223], v203 offset:45568
	ds_read_b64_tr_b16 v[224:225], v203 offset:48128
	ds_read_b64_tr_b16 v[226:227], v203 offset:50688
	ds_read_b64_tr_b16 v[228:229], v203 offset:43040
	ds_read_b64_tr_b16 v[230:231], v203 offset:45600
	ds_read_b64_tr_b16 v[232:233], v203 offset:48160
	ds_read_b64_tr_b16 v[234:235], v203 offset:50720
	ds_read_b64_tr_b16 v[236:237], v203 offset:43072
	ds_read_b64_tr_b16 v[238:239], v203 offset:45632
	ds_read_b64_tr_b16 v[240:241], v203 offset:48192
	ds_read_b64_tr_b16 v[242:243], v203 offset:50752
	ds_read_b64_tr_b16 v[244:245], v203 offset:43104
	ds_read_b64_tr_b16 v[246:247], v203 offset:45664
	v_exp_f32_e32 v24, v24
	v_exp_f32_e32 v25, v25
	v_exp_f32_e32 v26, v26
	v_exp_f32_e32 v27, v27
	v_exp_f32_e32 v28, v28
	v_exp_f32_e32 v29, v29
	v_exp_f32_e32 v30, v30
	v_exp_f32_e32 v31, v31
	v_exp_f32_e32 v32, v32
	v_exp_f32_e32 v33, v33
	v_exp_f32_e32 v34, v34
	v_exp_f32_e32 v35, v35
	v_exp_f32_e32 v36, v36
	v_exp_f32_e32 v37, v37
	v_exp_f32_e32 v38, v38
	v_exp_f32_e32 v39, v39
	v_cvt_pk_bf16_f32 v132, v24, v25
	v_cvt_pk_bf16_f32 v133, v26, v27
	v_cvt_pk_bf16_f32 v134, v28, v29
	v_cvt_pk_bf16_f32 v135, v30, v31
	v_cvt_pk_bf16_f32 v136, v32, v33
	v_cvt_pk_bf16_f32 v137, v34, v35
	v_cvt_pk_bf16_f32 v138, v36, v37
	v_cvt_pk_bf16_f32 v139, v38, v39
	v_add_f32_e32 v24, v24, v25
	v_add_f32_e32 v26, v26, v27
	v_add_f32_e32 v28, v28, v29
	v_add_f32_e32 v30, v30, v31
	v_add_f32_e32 v32, v32, v33
	v_add_f32_e32 v34, v34, v35
	v_add_f32_e32 v36, v36, v37
	v_add_f32_e32 v38, v38, v39
	v_add_f32_e32 v24, v24, v26
	v_add_f32_e32 v28, v28, v30
	v_add_f32_e32 v32, v32, v34
	v_add_f32_e32 v36, v36, v38
	v_add_f32_e32 v24, v24, v28
	v_add_f32_e32 v32, v32, v36
	v_add_f32_e32 v24, v24, v32
	v_add_f32_e32 v165, v165, v24
	v_exp_f32_e32 v40, v40
	v_exp_f32_e32 v41, v41
	v_exp_f32_e32 v42, v42
	v_exp_f32_e32 v43, v43
	v_exp_f32_e32 v44, v44
	v_exp_f32_e32 v45, v45
	v_exp_f32_e32 v46, v46
	v_exp_f32_e32 v47, v47
	v_exp_f32_e32 v212, v212
	v_exp_f32_e32 v213, v213
	v_exp_f32_e32 v214, v214
	v_exp_f32_e32 v215, v215
	v_exp_f32_e32 v216, v216
	v_exp_f32_e32 v217, v217
	v_exp_f32_e32 v218, v218
	v_exp_f32_e32 v219, v219
	v_cvt_pk_bf16_f32 v140, v40, v41
	v_cvt_pk_bf16_f32 v141, v42, v43
	v_cvt_pk_bf16_f32 v142, v44, v45
	v_cvt_pk_bf16_f32 v143, v46, v47
	v_cvt_pk_bf16_f32 v52, v212, v213
	v_cvt_pk_bf16_f32 v53, v214, v215
	v_cvt_pk_bf16_f32 v54, v216, v217
	v_cvt_pk_bf16_f32 v55, v218, v219
	v_add_f32_e32 v40, v40, v41
	v_add_f32_e32 v42, v42, v43
	v_add_f32_e32 v44, v44, v45
	v_add_f32_e32 v46, v46, v47
	v_add_f32_e32 v212, v212, v213
	v_add_f32_e32 v214, v214, v215
	v_add_f32_e32 v216, v216, v217
	v_add_f32_e32 v218, v218, v219
	v_add_f32_e32 v40, v40, v42
	v_add_f32_e32 v44, v44, v46
	v_add_f32_e32 v212, v212, v214
	v_add_f32_e32 v216, v216, v218
	v_add_f32_e32 v40, v40, v44
	v_add_f32_e32 v212, v212, v216
	v_add_f32_e32 v40, v40, v212
	v_add_f32_e32 v164, v164, v40
	s_waitcnt lgkmcnt(0)
	v_mfma_f32_16x16x32_bf16 v[96:99], v[220:223], v[132:135], v[96:99]
	v_mfma_f32_16x16x32_bf16 v[84:87], v[220:223], v[140:143], v[84:87]
	v_mfma_f32_16x16x32_bf16 v[96:99], v[224:227], v[136:139], v[96:99]
	v_mfma_f32_16x16x32_bf16 v[84:87], v[224:227], v[52:55], v[84:87]
	ds_read_b64_tr_b16 v[220:221], v203 offset:48224
	ds_read_b64_tr_b16 v[222:223], v203 offset:50784
	v_mfma_f32_16x16x32_bf16 v[88:91], v[228:231], v[132:135], v[88:91]
	v_mfma_f32_16x16x32_bf16 v[76:79], v[228:231], v[140:143], v[76:79]
	v_mfma_f32_16x16x32_bf16 v[88:91], v[232:235], v[136:139], v[88:91]
	v_mfma_f32_16x16x32_bf16 v[76:79], v[232:235], v[52:55], v[76:79]
	v_mfma_f32_16x16x32_bf16 v[92:95], v[236:239], v[132:135], v[92:95]
	v_mfma_f32_16x16x32_bf16 v[80:83], v[236:239], v[140:143], v[80:83]
	v_mfma_f32_16x16x32_bf16 v[92:95], v[240:243], v[136:139], v[92:95]
	v_mfma_f32_16x16x32_bf16 v[80:83], v[240:243], v[52:55], v[80:83]
	v_mfma_f32_16x16x32_bf16 v[48:51], v[244:247], v[132:135], v[48:51]
	v_mfma_f32_16x16x32_bf16 v[56:59], v[244:247], v[140:143], v[56:59]
	s_waitcnt lgkmcnt(0)
	v_mfma_f32_16x16x32_bf16 v[48:51], v[220:223], v[136:139], v[48:51]
	v_mfma_f32_16x16x32_bf16 v[56:59], v[220:223], v[52:55], v[56:59]
	s_branch .Lmla_bar5
